# v25 + gate sigmoid moved from the in-proj GEMM epilogue (VALU-bound, MFMA idle) into the gate-GEMM epilogue where it hides under memory waits; gates now stored pre-activation in bf16 and activated in
# baseline (speedup 1.0000x reference)
; __device__ __forceinline__ unsigned cvt_pk_bf16(float lo, float hi) { unsigned r; asm volatile("v_cvt_pk_bf16_f32 %0, %1, %2" : "=v"(r) : "v"(lo), "v"(hi)); return r; }
; __device__ __forceinline__ float bf_lo(unsigned w) { return __uint_as_float(w << 16); }
; __device__ __forceinline__ float bf_hi(unsigned w) { return __uint_as_float(w & 0xffff0000u); }
; #define EG_LOAD(slot, it) do { const size_t row_ = (size_t)(row0 + ((it) >> 2) * HALF + ((it) & 3) * 16); _Pragma("unroll") for (int bj = 0; bj < 2; ++bj) { \
;             g[slot][bj] = gld((const u32x4*)(G + row_ * ldg + col0 + bj * HALF)); o[slot][bj] = (u32x4){0u, 0u, 0u, 0u}; if (!first) o[slot][bj] = gld((const u32x4*)(MIX + row_ * ldm + col0 + bj * HALF)); } } while (0)
;     __device__ __forceinline__ void operator()(const f32x4 (&acc)[2][2][4][2], const Unit& u, int wr, int wc, int fr, int fq) const {
;     ...
;         EG_LOAD(0, 0);
; #pragma unroll
;         for (int it = 0; it < 8; ++it) { const int ai = it >> 2, m = it & 3, sl = it & 1; const size_t row = (size_t)(row0 + ai * HALF + m * 16);
;             if (it + 1 < 8) EG_LOAD(sl ^ 1, it + 1);
; #pragma unroll
;             for (int bj = 0; bj < 2; ++bj) { const u32x4 gg = g[sl][bj], oo = o[sl][bj]; const f32x4 v0 = acc[ai][bj][m][0], v1 = acc[ai][bj][m][1]; u32x4 w;
;                 w.x = cvt_pk_bf16(bf_lo(oo.x) + bf_lo(gg.x) * v0[0], bf_hi(oo.x) + bf_hi(gg.x) * v0[1]);
;                 w.y = cvt_pk_bf16(bf_lo(oo.y) + bf_lo(gg.y) * v0[2], bf_hi(oo.y) + bf_hi(gg.y) * v0[3]);
;                 w.z = cvt_pk_bf16(bf_lo(oo.z) + bf_lo(gg.z) * v1[0], bf_hi(oo.z) + bf_hi(gg.z) * v1[1]);
;                 w.w = cvt_pk_bf16(bf_lo(oo.w) + bf_lo(gg.w) * v1[2], bf_hi(oo.w) + bf_hi(gg.w) * v1[3]);
;                 gst((u32x4*)(MIX + row * ldm + col0 + bj * HALF), w); }
.LBB0_1375:
	s_waitcnt vmcnt(0)
	v_lshlrev_b32_e32 v175, 16, v158
	v_lshlrev_b32_e32 v206, 16, v154
	v_mul_f32_e32 v206, 0xbfb8aa3b, v206
	v_exp_f32_e32 v206, v206
	s_nop 0
	v_add_f32_e32 v206, 1.0, v206
	v_rcp_f32_e32 v206, v206
	s_nop 0
	v_fmac_f32_e32 v175, v126, v206
	v_and_b32_e32 v126, 0xffff0000, v158
	v_and_b32_e32 v154, 0xffff0000, v154
	v_mul_f32_e32 v154, 0xbfb8aa3b, v154
	v_exp_f32_e32 v154, v154
	s_nop 0
	v_add_f32_e32 v154, 1.0, v154
	v_rcp_f32_e32 v154, v154
	s_nop 0
	v_fmac_f32_e32 v126, v127, v154
	v_lshlrev_b32_e32 v127, 16, v159
	v_lshlrev_b32_e32 v154, 16, v155
	v_mul_f32_e32 v154, 0xbfb8aa3b, v154
	v_exp_f32_e32 v154, v154
	s_nop 0
	v_add_f32_e32 v154, 1.0, v154
	v_rcp_f32_e32 v154, v154
	s_nop 0
	v_fmac_f32_e32 v127, v128, v154
	v_and_b32_e32 v128, 0xffff0000, v159
	v_and_b32_e32 v154, 0xffff0000, v155
	v_mul_f32_e32 v154, 0xbfb8aa3b, v154
	v_exp_f32_e32 v154, v154
	s_nop 0
	v_add_f32_e32 v154, 1.0, v154
	v_rcp_f32_e32 v154, v154
	s_nop 0
	v_fmac_f32_e32 v128, v129, v154
	v_cvt_pk_bf16_f32 v126, v175, v126
	v_cvt_pk_bf16_f32 v127, v127, v128
	v_lshlrev_b32_e32 v128, 16, v160
	v_lshlrev_b32_e32 v129, 16, v156
	v_mul_f32_e32 v129, 0xbfb8aa3b, v129
	v_exp_f32_e32 v129, v129
	s_nop 0
	v_add_f32_e32 v129, 1.0, v129
	v_rcp_f32_e32 v129, v129
	s_nop 0
	v_fmac_f32_e32 v128, v122, v129
	v_and_b32_e32 v122, 0xffff0000, v160
	v_and_b32_e32 v129, 0xffff0000, v156
	v_mul_f32_e32 v129, 0xbfb8aa3b, v129
	v_exp_f32_e32 v129, v129
	s_nop 0
	v_add_f32_e32 v129, 1.0, v129
	v_rcp_f32_e32 v129, v129
	s_nop 0
	v_fmac_f32_e32 v122, v123, v129
	v_cvt_pk_bf16_f32 v128, v128, v122
	v_lshlrev_b32_e32 v122, 16, v161
	v_lshlrev_b32_e32 v123, 16, v157
	v_mul_f32_e32 v123, 0xbfb8aa3b, v123
	v_exp_f32_e32 v123, v123
	s_nop 0
	v_add_f32_e32 v123, 1.0, v123
	v_rcp_f32_e32 v123, v123
	s_nop 0
	v_fmac_f32_e32 v122, v124, v123
	v_and_b32_e32 v123, 0xffff0000, v161
	v_and_b32_e32 v124, 0xffff0000, v157
	v_mul_f32_e32 v124, 0xbfb8aa3b, v124
	v_exp_f32_e32 v124, v124
	s_nop 0
	v_add_f32_e32 v124, 1.0, v124
	v_rcp_f32_e32 v124, v124
	s_nop 0
	v_fmac_f32_e32 v123, v125, v124
	v_cvt_pk_bf16_f32 v129, v122, v123
	v_lshlrev_b32_e32 v122, 16, v146
	v_lshlrev_b32_e32 v123, 16, v150
	v_mul_f32_e32 v123, 0xbfb8aa3b, v123
	v_exp_f32_e32 v123, v123
	s_nop 0
	v_add_f32_e32 v123, 1.0, v123
	v_rcp_f32_e32 v123, v123
	s_nop 0
	v_fmac_f32_e32 v122, v118, v123
	v_and_b32_e32 v118, 0xffff0000, v146
	v_and_b32_e32 v123, 0xffff0000, v150
	v_mul_f32_e32 v123, 0xbfb8aa3b, v123
	v_exp_f32_e32 v123, v123
	s_nop 0
	v_add_f32_e32 v123, 1.0, v123
	v_rcp_f32_e32 v123, v123
	s_nop 0
	v_fmac_f32_e32 v118, v119, v123
	global_store_dwordx4 v[178:179], v[126:129], off
	v_cvt_pk_bf16_f32 v118, v122, v118
	v_lshlrev_b32_e32 v119, 16, v147
	v_lshlrev_b32_e32 v122, 16, v151
	v_mul_f32_e32 v122, 0xbfb8aa3b, v122
	v_exp_f32_e32 v122, v122
	s_nop 0
	v_add_f32_e32 v122, 1.0, v122
	v_rcp_f32_e32 v122, v122
	s_nop 0
	v_fmac_f32_e32 v119, v120, v122
	v_and_b32_e32 v120, 0xffff0000, v147
	v_and_b32_e32 v122, 0xffff0000, v151
	v_mul_f32_e32 v122, 0xbfb8aa3b, v122
	v_exp_f32_e32 v122, v122
	s_nop 0
	v_add_f32_e32 v122, 1.0, v122
	v_rcp_f32_e32 v122, v122
	s_nop 0
	v_fmac_f32_e32 v120, v121, v122
	v_cvt_pk_bf16_f32 v119, v119, v120
	v_lshlrev_b32_e32 v120, 16, v148
	v_lshlrev_b32_e32 v121, 16, v152
	v_mul_f32_e32 v121, 0xbfb8aa3b, v121
	v_exp_f32_e32 v121, v121
	s_nop 0
	v_add_f32_e32 v121, 1.0, v121
	v_rcp_f32_e32 v121, v121
	s_nop 0
	v_fmac_f32_e32 v120, v114, v121
	v_and_b32_e32 v114, 0xffff0000, v148
	v_and_b32_e32 v121, 0xffff0000, v152
	v_mul_f32_e32 v121, 0xbfb8aa3b, v121
	v_exp_f32_e32 v121, v121
	s_nop 0
	v_add_f32_e32 v121, 1.0, v121
	v_rcp_f32_e32 v121, v121
	s_nop 0
	v_fmac_f32_e32 v114, v115, v121
	v_cvt_pk_bf16_f32 v120, v120, v114
	v_lshlrev_b32_e32 v114, 16, v149
	v_lshlrev_b32_e32 v115, 16, v153
	v_mul_f32_e32 v115, 0xbfb8aa3b, v115
	v_exp_f32_e32 v115, v115
	s_nop 0
	v_add_f32_e32 v115, 1.0, v115
	v_rcp_f32_e32 v115, v115
	s_nop 0
	v_fmac_f32_e32 v114, v116, v115
	v_and_b32_e32 v115, 0xffff0000, v149
	v_and_b32_e32 v116, 0xffff0000, v153
	v_mul_f32_e32 v116, 0xbfb8aa3b, v116
	v_exp_f32_e32 v116, v116
	s_nop 0
	v_add_f32_e32 v116, 1.0, v116
	v_rcp_f32_e32 v116, v116
	s_nop 0
	v_fmac_f32_e32 v115, v117, v116
	v_cvt_pk_bf16_f32 v121, v114, v115
	v_or_b32_e32 v114, 32, v174
	v_mov_b64_e32 v[116:117], s[18:19]
	global_store_dwordx4 v[178:179], v[118:121], off offset:256
	v_mad_i64_i32 v[116:117], s[50:51], v114, s81, v[116:117]
	v_lshl_add_u64 v[116:117], v[116:117], 0, v[172:173]
	global_load_dwordx4 v[122:125], v[116:117], off
	v_ashrrev_i32_e32 v115, 31, v114
	v_lshlrev_b64 v[114:115], 11, v[114:115]
	v_lshl_add_u64 v[114:115], s[12:13], 0, v[114:115]
	v_lshl_add_u64 v[146:147], v[114:115], 0, v[172:173]
	v_mov_b32_e32 v114, 0
	s_and_b64 vcc, exec, s[42:43]
	v_mov_b32_e32 v126, 0
	v_mov_b32_e32 v127, 0
	v_mov_b32_e32 v128, 0
	v_mov_b32_e32 v129, 0
	s_cbranch_vccnz .LBB0_1377
	global_load_dwordx4 v[126:129], v[146:147], off

; __device__ __forceinline__ unsigned cvt_pk_bf16(float lo, float hi) { unsigned r; asm volatile("v_cvt_pk_bf16_f32 %0, %1, %2" : "=v"(r) : "v"(lo), "v"(hi)); return r; }
; __device__ __forceinline__ float bf_lo(unsigned w) { return __uint_as_float(w << 16); }
; __device__ __forceinline__ float bf_hi(unsigned w) { return __uint_as_float(w & 0xffff0000u); }
; #define EG_LOAD(slot, it) do { const size_t row_ = (size_t)(row0 + ((it) >> 2) * HALF + ((it) & 3) * 16); _Pragma("unroll") for (int bj = 0; bj < 2; ++bj) { \
;             g[slot][bj] = gld((const u32x4*)(G + row_ * ldg + col0 + bj * HALF)); o[slot][bj] = (u32x4){0u, 0u, 0u, 0u}; if (!first) o[slot][bj] = gld((const u32x4*)(MIX + row_ * ldm + col0 + bj * HALF)); } } while (0)
;     __device__ __forceinline__ void operator()(const f32x4 (&acc)[2][2][4][2], const Unit& u, int wr, int wc, int fr, int fq) const {
;     ...
;         EG_LOAD(0, 0);
; #pragma unroll
;         for (int it = 0; it < 8; ++it) { const int ai = it >> 2, m = it & 3, sl = it & 1; const size_t row = (size_t)(row0 + ai * HALF + m * 16);
;             if (it + 1 < 8) EG_LOAD(sl ^ 1, it + 1);
; #pragma unroll
;             for (int bj = 0; bj < 2; ++bj) { const u32x4 gg = g[sl][bj], oo = o[sl][bj]; const f32x4 v0 = acc[ai][bj][m][0], v1 = acc[ai][bj][m][1]; u32x4 w;
;                 w.x = cvt_pk_bf16(bf_lo(oo.x) + bf_lo(gg.x) * v0[0], bf_hi(oo.x) + bf_hi(gg.x) * v0[1]);
;                 w.y = cvt_pk_bf16(bf_lo(oo.y) + bf_lo(gg.y) * v0[2], bf_hi(oo.y) + bf_hi(gg.y) * v0[3]);
;                 w.z = cvt_pk_bf16(bf_lo(oo.z) + bf_lo(gg.z) * v1[0], bf_hi(oo.z) + bf_hi(gg.z) * v1[1]);
;                 w.w = cvt_pk_bf16(bf_lo(oo.w) + bf_lo(gg.w) * v1[2], bf_hi(oo.w) + bf_hi(gg.w) * v1[3]);
;                 gst((u32x4*)(MIX + row * ldm + col0 + bj * HALF), w); }
.LBB0_1379:
	v_lshlrev_b32_e32 v148, 16, v142
	v_lshlrev_b32_e32 v149, 16, v138
	v_mul_f32_e32 v149, 0xbfb8aa3b, v149
	v_exp_f32_e32 v149, v149
	s_nop 0
	v_add_f32_e32 v149, 1.0, v149
	v_rcp_f32_e32 v149, v149
	s_nop 0
	v_fmac_f32_e32 v148, v110, v149
	v_and_b32_e32 v110, 0xffff0000, v142
	v_and_b32_e32 v138, 0xffff0000, v138
	v_mul_f32_e32 v138, 0xbfb8aa3b, v138
	v_exp_f32_e32 v138, v138
	s_nop 0
	v_add_f32_e32 v138, 1.0, v138
	v_rcp_f32_e32 v138, v138
	s_nop 0
	v_fmac_f32_e32 v110, v111, v138
	v_lshlrev_b32_e32 v111, 16, v143
	v_lshlrev_b32_e32 v138, 16, v139
	v_mul_f32_e32 v138, 0xbfb8aa3b, v138
	v_exp_f32_e32 v138, v138
	s_nop 0
	v_add_f32_e32 v138, 1.0, v138
	v_rcp_f32_e32 v138, v138
	s_nop 0
	v_fmac_f32_e32 v111, v112, v138
	v_and_b32_e32 v112, 0xffff0000, v143
	v_and_b32_e32 v138, 0xffff0000, v139
	v_mul_f32_e32 v138, 0xbfb8aa3b, v138
	v_exp_f32_e32 v138, v138
	s_nop 0
	v_add_f32_e32 v138, 1.0, v138
	v_rcp_f32_e32 v138, v138
	s_nop 0
	v_fmac_f32_e32 v112, v113, v138
	v_cvt_pk_bf16_f32 v110, v148, v110
	v_cvt_pk_bf16_f32 v111, v111, v112
	v_lshlrev_b32_e32 v112, 16, v144
	v_lshlrev_b32_e32 v113, 16, v140
	v_mul_f32_e32 v113, 0xbfb8aa3b, v113
	v_exp_f32_e32 v113, v113
	s_nop 0
	v_add_f32_e32 v113, 1.0, v113
	v_rcp_f32_e32 v113, v113
	s_nop 0
	v_fmac_f32_e32 v112, v106, v113
	v_and_b32_e32 v106, 0xffff0000, v144
	v_and_b32_e32 v113, 0xffff0000, v140
	v_mul_f32_e32 v113, 0xbfb8aa3b, v113
	v_exp_f32_e32 v113, v113
	s_nop 0
	v_add_f32_e32 v113, 1.0, v113
	v_rcp_f32_e32 v113, v113
	s_nop 0
	v_fmac_f32_e32 v106, v107, v113
	v_cvt_pk_bf16_f32 v112, v112, v106
	v_lshlrev_b32_e32 v106, 16, v145
	v_lshlrev_b32_e32 v107, 16, v141
	v_mul_f32_e32 v107, 0xbfb8aa3b, v107
	v_exp_f32_e32 v107, v107
	s_nop 0
	v_add_f32_e32 v107, 1.0, v107
	v_rcp_f32_e32 v107, v107
	s_nop 0
	v_fmac_f32_e32 v106, v108, v107
	v_and_b32_e32 v107, 0xffff0000, v145
	v_and_b32_e32 v108, 0xffff0000, v141
	v_mul_f32_e32 v108, 0xbfb8aa3b, v108
	v_exp_f32_e32 v108, v108
	s_nop 0
	v_add_f32_e32 v108, 1.0, v108
	v_rcp_f32_e32 v108, v108
	s_nop 0
	v_fmac_f32_e32 v107, v109, v108
	v_cvt_pk_bf16_f32 v113, v106, v107
	v_lshlrev_b32_e32 v106, 16, v130
	v_lshlrev_b32_e32 v107, 16, v134
	v_mul_f32_e32 v107, 0xbfb8aa3b, v107
	v_exp_f32_e32 v107, v107
	s_nop 0
	v_add_f32_e32 v107, 1.0, v107
	v_rcp_f32_e32 v107, v107
	s_nop 0
	v_fmac_f32_e32 v106, v102, v107
	v_and_b32_e32 v102, 0xffff0000, v130
	v_and_b32_e32 v107, 0xffff0000, v134
	v_mul_f32_e32 v107, 0xbfb8aa3b, v107
	v_exp_f32_e32 v107, v107
	s_nop 0
	v_add_f32_e32 v107, 1.0, v107
	v_rcp_f32_e32 v107, v107
	s_nop 0
	v_fmac_f32_e32 v102, v103, v107
	global_store_dwordx4 v[176:177], v[110:113], off
	v_cvt_pk_bf16_f32 v102, v106, v102
	v_lshlrev_b32_e32 v103, 16, v131
	v_lshlrev_b32_e32 v106, 16, v135
	v_mul_f32_e32 v106, 0xbfb8aa3b, v106
	v_exp_f32_e32 v106, v106
	s_nop 0
	v_add_f32_e32 v106, 1.0, v106
	v_rcp_f32_e32 v106, v106
	s_nop 0
	v_fmac_f32_e32 v103, v104, v106
	v_and_b32_e32 v104, 0xffff0000, v131
	v_and_b32_e32 v106, 0xffff0000, v135
	v_mul_f32_e32 v106, 0xbfb8aa3b, v106
	v_exp_f32_e32 v106, v106
	s_nop 0
	v_add_f32_e32 v106, 1.0, v106
	v_rcp_f32_e32 v106, v106
	s_nop 0
	v_fmac_f32_e32 v104, v105, v106
	v_cvt_pk_bf16_f32 v103, v103, v104
	v_lshlrev_b32_e32 v104, 16, v132
	v_lshlrev_b32_e32 v105, 16, v136
	v_mul_f32_e32 v105, 0xbfb8aa3b, v105
	v_exp_f32_e32 v105, v105
	s_nop 0
	v_add_f32_e32 v105, 1.0, v105
	v_rcp_f32_e32 v105, v105
	s_nop 0
	v_fmac_f32_e32 v104, v98, v105
	v_and_b32_e32 v98, 0xffff0000, v132
	v_and_b32_e32 v105, 0xffff0000, v136
	v_mul_f32_e32 v105, 0xbfb8aa3b, v105
	v_exp_f32_e32 v105, v105
	s_nop 0
	v_add_f32_e32 v105, 1.0, v105
	v_rcp_f32_e32 v105, v105
	s_nop 0
	v_fmac_f32_e32 v98, v99, v105
	v_cvt_pk_bf16_f32 v104, v104, v98
	v_lshlrev_b32_e32 v98, 16, v133
	v_lshlrev_b32_e32 v99, 16, v137
	v_mul_f32_e32 v99, 0xbfb8aa3b, v99
	v_exp_f32_e32 v99, v99
	s_nop 0
	v_add_f32_e32 v99, 1.0, v99
	v_rcp_f32_e32 v99, v99
	s_nop 0
	v_fmac_f32_e32 v98, v100, v99
	v_and_b32_e32 v99, 0xffff0000, v133
	v_and_b32_e32 v100, 0xffff0000, v137
	v_mul_f32_e32 v100, 0xbfb8aa3b, v100
	v_exp_f32_e32 v100, v100
	s_nop 0
	v_add_f32_e32 v100, 1.0, v100
	v_rcp_f32_e32 v100, v100
	s_nop 0
	v_fmac_f32_e32 v99, v101, v100
	v_cvt_pk_bf16_f32 v105, v98, v99
	v_or_b32_e32 v98, 48, v174
	v_mov_b64_e32 v[100:101], s[18:19]
	global_store_dwordx4 v[176:177], v[102:105], off offset:256
	v_mad_i64_i32 v[100:101], s[50:51], v98, s81, v[100:101]
	v_lshl_add_u64 v[100:101], v[100:101], 0, v[172:173]
	global_load_dwordx4 v[106:109], v[100:101], off
	v_ashrrev_i32_e32 v99, 31, v98
	v_lshlrev_b64 v[98:99], 11, v[98:99]
	v_lshl_add_u64 v[98:99], s[12:13], 0, v[98:99]
	v_lshl_add_u64 v[130:131], v[98:99], 0, v[172:173]
	v_mov_b32_e32 v98, 0
	s_and_b64 vcc, exec, s[42:43]
	v_mov_b32_e32 v110, 0
	v_mov_b32_e32 v111, 0
	v_mov_b32_e32 v112, 0
	v_mov_b32_e32 v113, 0
	s_cbranch_vccnz .LBB0_1381
	global_load_dwordx4 v[110:113], v[130:131], off

; __device__ __forceinline__ unsigned cvt_pk_bf16(float lo, float hi) { unsigned r; asm volatile("v_cvt_pk_bf16_f32 %0, %1, %2" : "=v"(r) : "v"(lo), "v"(hi)); return r; }
; __device__ __forceinline__ float bf_lo(unsigned w) { return __uint_as_float(w << 16); }
; __device__ __forceinline__ float bf_hi(unsigned w) { return __uint_as_float(w & 0xffff0000u); }
;     __device__ __forceinline__ void operator()(const f32x4 (&acc)[2][2][4][2], const Unit& u, int wr, int wc, int fr, int fq) const {
;     ...
;             for (int bj = 0; bj < 2; ++bj) { const u32x4 gg = g[sl][bj], oo = o[sl][bj]; const f32x4 v0 = acc[ai][bj][m][0], v1 = acc[ai][bj][m][1]; u32x4 w;
;                 w.x = cvt_pk_bf16(bf_lo(oo.x) + bf_lo(gg.x) * v0[0], bf_hi(oo.x) + bf_hi(gg.x) * v0[1]);
;                 w.y = cvt_pk_bf16(bf_lo(oo.y) + bf_lo(gg.y) * v0[2], bf_hi(oo.y) + bf_hi(gg.y) * v0[3]);
;                 w.z = cvt_pk_bf16(bf_lo(oo.z) + bf_lo(gg.z) * v1[0], bf_hi(oo.z) + bf_hi(gg.z) * v1[1]);
;                 w.w = cvt_pk_bf16(bf_lo(oo.w) + bf_lo(gg.w) * v1[2], bf_hi(oo.w) + bf_hi(gg.w) * v1[3]);
;                 gst((u32x4*)(MIX + row * ldm + col0 + bj * HALF), w); }
.Lmy_gd_9:
	v_lshlrev_b32_e32 v132, 16, v126
	v_lshlrev_b32_e32 v133, 16, v122
	v_mul_f32_e32 v133, 0xbfb8aa3b, v133
	v_exp_f32_e32 v133, v133
	s_nop 0
	v_add_f32_e32 v133, 1.0, v133
	v_rcp_f32_e32 v133, v133
	s_nop 0
	v_fmac_f32_e32 v132, v94, v133
	v_and_b32_e32 v94, 0xffff0000, v126
	v_and_b32_e32 v122, 0xffff0000, v122
	v_mul_f32_e32 v122, 0xbfb8aa3b, v122
	v_exp_f32_e32 v122, v122
	s_nop 0
	v_add_f32_e32 v122, 1.0, v122
	v_rcp_f32_e32 v122, v122
	s_nop 0
	v_fmac_f32_e32 v94, v95, v122
	v_lshlrev_b32_e32 v95, 16, v127
	v_lshlrev_b32_e32 v122, 16, v123
	v_mul_f32_e32 v122, 0xbfb8aa3b, v122
	v_exp_f32_e32 v122, v122
	s_nop 0
	v_add_f32_e32 v122, 1.0, v122
	v_rcp_f32_e32 v122, v122
	s_nop 0
	v_fmac_f32_e32 v95, v96, v122
	v_and_b32_e32 v96, 0xffff0000, v127
	v_and_b32_e32 v122, 0xffff0000, v123
	v_mul_f32_e32 v122, 0xbfb8aa3b, v122
	v_exp_f32_e32 v122, v122
	s_nop 0
	v_add_f32_e32 v122, 1.0, v122
	v_rcp_f32_e32 v122, v122
	s_nop 0
	v_fmac_f32_e32 v96, v97, v122
	v_cvt_pk_bf16_f32 v94, v132, v94
	v_cvt_pk_bf16_f32 v95, v95, v96
	v_lshlrev_b32_e32 v96, 16, v128
	v_lshlrev_b32_e32 v97, 16, v124
	v_mul_f32_e32 v97, 0xbfb8aa3b, v97
	v_exp_f32_e32 v97, v97
	s_nop 0
	v_add_f32_e32 v97, 1.0, v97
	v_rcp_f32_e32 v97, v97
	s_nop 0
	v_fmac_f32_e32 v96, v90, v97
	v_and_b32_e32 v90, 0xffff0000, v128
	v_and_b32_e32 v97, 0xffff0000, v124
	v_mul_f32_e32 v97, 0xbfb8aa3b, v97
	v_exp_f32_e32 v97, v97
	s_nop 0
	v_add_f32_e32 v97, 1.0, v97
	v_rcp_f32_e32 v97, v97
	s_nop 0
	v_fmac_f32_e32 v90, v91, v97
	v_cvt_pk_bf16_f32 v96, v96, v90
	v_lshlrev_b32_e32 v90, 16, v129
	v_lshlrev_b32_e32 v91, 16, v125
	v_mul_f32_e32 v91, 0xbfb8aa3b, v91
	v_exp_f32_e32 v91, v91
	s_nop 0
	v_add_f32_e32 v91, 1.0, v91
	v_rcp_f32_e32 v91, v91
	s_nop 0
	v_fmac_f32_e32 v90, v92, v91
	v_and_b32_e32 v91, 0xffff0000, v129
	v_and_b32_e32 v92, 0xffff0000, v125
	v_mul_f32_e32 v92, 0xbfb8aa3b, v92
	v_exp_f32_e32 v92, v92
	s_nop 0
	v_add_f32_e32 v92, 1.0, v92
	v_rcp_f32_e32 v92, v92
	s_nop 0
	v_fmac_f32_e32 v91, v93, v92
	v_cvt_pk_bf16_f32 v97, v90, v91
	s_cbranch_vccnz .Lmy_gf_8
	s_waitcnt vmcnt(6)
	s_branch .Lmy_gd_8

; __device__ __forceinline__ unsigned cvt_pk_bf16(float lo, float hi) { unsigned r; asm volatile("v_cvt_pk_bf16_f32 %0, %1, %2" : "=v"(r) : "v"(lo), "v"(hi)); return r; }
; __device__ __forceinline__ float bf_lo(unsigned w) { return __uint_as_float(w << 16); }
; __device__ __forceinline__ float bf_hi(unsigned w) { return __uint_as_float(w & 0xffff0000u); }
; #define EG_LOAD(slot, it) do { const size_t row_ = (size_t)(row0 + ((it) >> 2) * HALF + ((it) & 3) * 16); _Pragma("unroll") for (int bj = 0; bj < 2; ++bj) { \
;             g[slot][bj] = gld((const u32x4*)(G + row_ * ldg + col0 + bj * HALF)); o[slot][bj] = (u32x4){0u, 0u, 0u, 0u}; if (!first) o[slot][bj] = gld((const u32x4*)(MIX + row_ * ldm + col0 + bj * HALF)); } } while (0)
;     __device__ __forceinline__ void operator()(const f32x4 (&acc)[2][2][4][2], const Unit& u, int wr, int wc, int fr, int fq) const {
;     ...
;         EG_LOAD(0, 0);
; #pragma unroll
;         for (int it = 0; it < 8; ++it) { const int ai = it >> 2, m = it & 3, sl = it & 1; const size_t row = (size_t)(row0 + ai * HALF + m * 16);
;             if (it + 1 < 8) EG_LOAD(sl ^ 1, it + 1);
; #pragma unroll
;             for (int bj = 0; bj < 2; ++bj) { const u32x4 gg = g[sl][bj], oo = o[sl][bj]; const f32x4 v0 = acc[ai][bj][m][0], v1 = acc[ai][bj][m][1]; u32x4 w;
;                 w.x = cvt_pk_bf16(bf_lo(oo.x) + bf_lo(gg.x) * v0[0], bf_hi(oo.x) + bf_hi(gg.x) * v0[1]);
;                 w.y = cvt_pk_bf16(bf_lo(oo.y) + bf_lo(gg.y) * v0[2], bf_hi(oo.y) + bf_hi(gg.y) * v0[3]);
;                 w.z = cvt_pk_bf16(bf_lo(oo.z) + bf_lo(gg.z) * v1[0], bf_hi(oo.z) + bf_hi(gg.z) * v1[1]);
;                 w.w = cvt_pk_bf16(bf_lo(oo.w) + bf_lo(gg.w) * v1[2], bf_hi(oo.w) + bf_hi(gg.w) * v1[3]);
;                 gst((u32x4*)(MIX + row * ldm + col0 + bj * HALF), w); }
.Lmy_gd_8:
	v_lshlrev_b32_e32 v90, 16, v114
	v_lshlrev_b32_e32 v91, 16, v118
	v_mul_f32_e32 v91, 0xbfb8aa3b, v91
	v_exp_f32_e32 v91, v91
	s_nop 0
	v_add_f32_e32 v91, 1.0, v91
	v_rcp_f32_e32 v91, v91
	s_nop 0
	v_fmac_f32_e32 v90, v86, v91
	v_and_b32_e32 v86, 0xffff0000, v114
	v_and_b32_e32 v91, 0xffff0000, v118
	v_mul_f32_e32 v91, 0xbfb8aa3b, v91
	v_exp_f32_e32 v91, v91
	s_nop 0
	v_add_f32_e32 v91, 1.0, v91
	v_rcp_f32_e32 v91, v91
	s_nop 0
	v_fmac_f32_e32 v86, v87, v91
	global_store_dwordx4 v[146:147], v[94:97], off
	v_cvt_pk_bf16_f32 v86, v90, v86
	v_lshlrev_b32_e32 v87, 16, v115
	v_lshlrev_b32_e32 v90, 16, v119
	v_mul_f32_e32 v90, 0xbfb8aa3b, v90
	v_exp_f32_e32 v90, v90
	s_nop 0
	v_add_f32_e32 v90, 1.0, v90
	v_rcp_f32_e32 v90, v90
	s_nop 0
	v_fmac_f32_e32 v87, v88, v90
	v_and_b32_e32 v88, 0xffff0000, v115
	v_and_b32_e32 v90, 0xffff0000, v119
	v_mul_f32_e32 v90, 0xbfb8aa3b, v90
	v_exp_f32_e32 v90, v90
	s_nop 0
	v_add_f32_e32 v90, 1.0, v90
	v_rcp_f32_e32 v90, v90
	s_nop 0
	v_fmac_f32_e32 v88, v89, v90
	v_cvt_pk_bf16_f32 v87, v87, v88
	v_lshlrev_b32_e32 v88, 16, v116
	v_lshlrev_b32_e32 v89, 16, v120
	v_mul_f32_e32 v89, 0xbfb8aa3b, v89
	v_exp_f32_e32 v89, v89
	s_nop 0
	v_add_f32_e32 v89, 1.0, v89
	v_rcp_f32_e32 v89, v89
	s_nop 0
	v_fmac_f32_e32 v88, v82, v89
	v_and_b32_e32 v82, 0xffff0000, v116
	v_and_b32_e32 v89, 0xffff0000, v120
	v_mul_f32_e32 v89, 0xbfb8aa3b, v89
	v_exp_f32_e32 v89, v89
	s_nop 0
	v_add_f32_e32 v89, 1.0, v89
	v_rcp_f32_e32 v89, v89
	s_nop 0
	v_fmac_f32_e32 v82, v83, v89
	v_cvt_pk_bf16_f32 v88, v88, v82
	v_lshlrev_b32_e32 v82, 16, v117
	v_lshlrev_b32_e32 v83, 16, v121
	v_mul_f32_e32 v83, 0xbfb8aa3b, v83
	v_exp_f32_e32 v83, v83
	s_nop 0
	v_add_f32_e32 v83, 1.0, v83
	v_rcp_f32_e32 v83, v83
	s_nop 0
	v_fmac_f32_e32 v82, v84, v83
	v_and_b32_e32 v83, 0xffff0000, v117
	v_and_b32_e32 v84, 0xffff0000, v121
	v_mul_f32_e32 v84, 0xbfb8aa3b, v84
	v_exp_f32_e32 v84, v84
	s_nop 0
	v_add_f32_e32 v84, 1.0, v84
	v_rcp_f32_e32 v84, v84
	s_nop 0
	v_fmac_f32_e32 v83, v85, v84
	v_cvt_pk_bf16_f32 v89, v82, v83
	v_add_u32_e32 v114, 0x80, v174
	v_mov_b64_e32 v[82:83], s[18:19]
	global_store_dwordx4 v[146:147], v[86:89], off offset:256
	v_mad_i64_i32 v[82:83], s[50:51], v114, s81, v[82:83]
	v_lshl_add_u64 v[84:85], v[82:83], 0, v[172:173]
	global_load_dwordx4 v[90:93], v[84:85], off
	v_ashrrev_i32_e32 v115, 31, v114
	v_lshlrev_b64 v[82:83], 11, v[114:115]
	v_lshl_add_u64 v[82:83], s[12:13], 0, v[82:83]
	v_lshl_add_u64 v[116:117], v[82:83], 0, v[172:173]
	v_mov_b32_e32 v82, 0
	s_and_b64 vcc, exec, s[42:43]
	v_mov_b32_e32 v94, 0
	v_mov_b32_e32 v95, 0
	v_mov_b32_e32 v96, 0
	v_mov_b32_e32 v97, 0
	s_cbranch_vccnz .LBB0_1385
	global_load_dwordx4 v[94:97], v[116:117], off

; __device__ __forceinline__ unsigned cvt_pk_bf16(float lo, float hi) { unsigned r; asm volatile("v_cvt_pk_bf16_f32 %0, %1, %2" : "=v"(r) : "v"(lo), "v"(hi)); return r; }
; __device__ __forceinline__ float bf_lo(unsigned w) { return __uint_as_float(w << 16); }
; __device__ __forceinline__ float bf_hi(unsigned w) { return __uint_as_float(w & 0xffff0000u); }
;     __device__ __forceinline__ void operator()(const f32x4 (&acc)[2][2][4][2], const Unit& u, int wr, int wc, int fr, int fq) const {
;     ...
;             for (int bj = 0; bj < 2; ++bj) { const u32x4 gg = g[sl][bj], oo = o[sl][bj]; const f32x4 v0 = acc[ai][bj][m][0], v1 = acc[ai][bj][m][1]; u32x4 w;
;                 w.x = cvt_pk_bf16(bf_lo(oo.x) + bf_lo(gg.x) * v0[0], bf_hi(oo.x) + bf_hi(gg.x) * v0[1]);
;                 w.y = cvt_pk_bf16(bf_lo(oo.y) + bf_lo(gg.y) * v0[2], bf_hi(oo.y) + bf_hi(gg.y) * v0[3]);
;                 w.z = cvt_pk_bf16(bf_lo(oo.z) + bf_lo(gg.z) * v1[0], bf_hi(oo.z) + bf_hi(gg.z) * v1[1]);
;                 w.w = cvt_pk_bf16(bf_lo(oo.w) + bf_lo(gg.w) * v1[2], bf_hi(oo.w) + bf_hi(gg.w) * v1[3]);
;                 gst((u32x4*)(MIX + row * ldm + col0 + bj * HALF), w); }
.Lmy_gd_7:
	v_lshlrev_b32_e32 v115, 16, v110
	v_lshlrev_b32_e32 v118, 16, v106
	v_mul_f32_e32 v118, 0xbfb8aa3b, v118
	v_exp_f32_e32 v118, v118
	s_nop 0
	v_add_f32_e32 v118, 1.0, v118
	v_rcp_f32_e32 v118, v118
	s_nop 0
	v_fmac_f32_e32 v115, v78, v118
	v_and_b32_e32 v78, 0xffff0000, v110
	v_and_b32_e32 v106, 0xffff0000, v106
	v_mul_f32_e32 v106, 0xbfb8aa3b, v106
	v_exp_f32_e32 v106, v106
	s_nop 0
	v_add_f32_e32 v106, 1.0, v106
	v_rcp_f32_e32 v106, v106
	s_nop 0
	v_fmac_f32_e32 v78, v79, v106
	v_lshlrev_b32_e32 v79, 16, v111
	v_lshlrev_b32_e32 v106, 16, v107
	v_mul_f32_e32 v106, 0xbfb8aa3b, v106
	v_exp_f32_e32 v106, v106
	s_nop 0
	v_add_f32_e32 v106, 1.0, v106
	v_rcp_f32_e32 v106, v106
	s_nop 0
	v_fmac_f32_e32 v79, v80, v106
	v_and_b32_e32 v80, 0xffff0000, v111
	v_and_b32_e32 v106, 0xffff0000, v107
	v_mul_f32_e32 v106, 0xbfb8aa3b, v106
	v_exp_f32_e32 v106, v106
	s_nop 0
	v_add_f32_e32 v106, 1.0, v106
	v_rcp_f32_e32 v106, v106
	s_nop 0
	v_fmac_f32_e32 v80, v81, v106
	v_cvt_pk_bf16_f32 v78, v115, v78
	v_cvt_pk_bf16_f32 v79, v79, v80
	v_lshlrev_b32_e32 v80, 16, v112
	v_lshlrev_b32_e32 v81, 16, v108
	v_mul_f32_e32 v81, 0xbfb8aa3b, v81
	v_exp_f32_e32 v81, v81
	s_nop 0
	v_add_f32_e32 v81, 1.0, v81
	v_rcp_f32_e32 v81, v81
	s_nop 0
	v_fmac_f32_e32 v80, v74, v81
	v_and_b32_e32 v74, 0xffff0000, v112
	v_and_b32_e32 v81, 0xffff0000, v108
	v_mul_f32_e32 v81, 0xbfb8aa3b, v81
	v_exp_f32_e32 v81, v81
	s_nop 0
	v_add_f32_e32 v81, 1.0, v81
	v_rcp_f32_e32 v81, v81
	s_nop 0
	v_fmac_f32_e32 v74, v75, v81
	v_cvt_pk_bf16_f32 v80, v80, v74
	v_lshlrev_b32_e32 v74, 16, v113
	v_lshlrev_b32_e32 v75, 16, v109
	v_mul_f32_e32 v75, 0xbfb8aa3b, v75
	v_exp_f32_e32 v75, v75
	s_nop 0
	v_add_f32_e32 v75, 1.0, v75
	v_rcp_f32_e32 v75, v75
	s_nop 0
	v_fmac_f32_e32 v74, v76, v75
	v_and_b32_e32 v75, 0xffff0000, v113
	v_and_b32_e32 v76, 0xffff0000, v109
	v_mul_f32_e32 v76, 0xbfb8aa3b, v76
	v_exp_f32_e32 v76, v76
	s_nop 0
	v_add_f32_e32 v76, 1.0, v76
	v_rcp_f32_e32 v76, v76
	s_nop 0
	v_fmac_f32_e32 v75, v77, v76
	v_cvt_pk_bf16_f32 v81, v74, v75
	s_cbranch_vccnz .Lmy_gf_6
	s_waitcnt vmcnt(6)
	s_branch .Lmy_gd_6

; __device__ __forceinline__ unsigned cvt_pk_bf16(float lo, float hi) { unsigned r; asm volatile("v_cvt_pk_bf16_f32 %0, %1, %2" : "=v"(r) : "v"(lo), "v"(hi)); return r; }
; __device__ __forceinline__ float bf_lo(unsigned w) { return __uint_as_float(w << 16); }
; __device__ __forceinline__ float bf_hi(unsigned w) { return __uint_as_float(w & 0xffff0000u); }
; #define EG_LOAD(slot, it) do { const size_t row_ = (size_t)(row0 + ((it) >> 2) * HALF + ((it) & 3) * 16); _Pragma("unroll") for (int bj = 0; bj < 2; ++bj) { \
;             g[slot][bj] = gld((const u32x4*)(G + row_ * ldg + col0 + bj * HALF)); o[slot][bj] = (u32x4){0u, 0u, 0u, 0u}; if (!first) o[slot][bj] = gld((const u32x4*)(MIX + row_ * ldm + col0 + bj * HALF)); } } while (0)
;     __device__ __forceinline__ void operator()(const f32x4 (&acc)[2][2][4][2], const Unit& u, int wr, int wc, int fr, int fq) const {
;     ...
;         EG_LOAD(0, 0);
; #pragma unroll
;         for (int it = 0; it < 8; ++it) { const int ai = it >> 2, m = it & 3, sl = it & 1; const size_t row = (size_t)(row0 + ai * HALF + m * 16);
;             if (it + 1 < 8) EG_LOAD(sl ^ 1, it + 1);
; #pragma unroll
;             for (int bj = 0; bj < 2; ++bj) { const u32x4 gg = g[sl][bj], oo = o[sl][bj]; const f32x4 v0 = acc[ai][bj][m][0], v1 = acc[ai][bj][m][1]; u32x4 w;
;                 w.x = cvt_pk_bf16(bf_lo(oo.x) + bf_lo(gg.x) * v0[0], bf_hi(oo.x) + bf_hi(gg.x) * v0[1]);
;                 w.y = cvt_pk_bf16(bf_lo(oo.y) + bf_lo(gg.y) * v0[2], bf_hi(oo.y) + bf_hi(gg.y) * v0[3]);
;                 w.z = cvt_pk_bf16(bf_lo(oo.z) + bf_lo(gg.z) * v1[0], bf_hi(oo.z) + bf_hi(gg.z) * v1[1]);
;                 w.w = cvt_pk_bf16(bf_lo(oo.w) + bf_lo(gg.w) * v1[2], bf_hi(oo.w) + bf_hi(gg.w) * v1[3]);
;                 gst((u32x4*)(MIX + row * ldm + col0 + bj * HALF), w); }
.Lmy_gd_6:
	v_lshlrev_b32_e32 v74, 16, v98
	v_lshlrev_b32_e32 v75, 16, v102
	v_mul_f32_e32 v75, 0xbfb8aa3b, v75
	v_exp_f32_e32 v75, v75
	s_nop 0
	v_add_f32_e32 v75, 1.0, v75
	v_rcp_f32_e32 v75, v75
	s_nop 0
	v_fmac_f32_e32 v74, v70, v75
	v_and_b32_e32 v70, 0xffff0000, v98
	v_and_b32_e32 v75, 0xffff0000, v102
	v_mul_f32_e32 v75, 0xbfb8aa3b, v75
	v_exp_f32_e32 v75, v75
	s_nop 0
	v_add_f32_e32 v75, 1.0, v75
	v_rcp_f32_e32 v75, v75
	s_nop 0
	v_fmac_f32_e32 v70, v71, v75
	global_store_dwordx4 v[130:131], v[78:81], off
	v_cvt_pk_bf16_f32 v70, v74, v70
	v_lshlrev_b32_e32 v71, 16, v99
	v_lshlrev_b32_e32 v74, 16, v103
	v_mul_f32_e32 v74, 0xbfb8aa3b, v74
	v_exp_f32_e32 v74, v74
	s_nop 0
	v_add_f32_e32 v74, 1.0, v74
	v_rcp_f32_e32 v74, v74
	s_nop 0
	v_fmac_f32_e32 v71, v72, v74
	v_and_b32_e32 v72, 0xffff0000, v99
	v_and_b32_e32 v74, 0xffff0000, v103
	v_mul_f32_e32 v74, 0xbfb8aa3b, v74
	v_exp_f32_e32 v74, v74
	s_nop 0
	v_add_f32_e32 v74, 1.0, v74
	v_rcp_f32_e32 v74, v74
	s_nop 0
	v_fmac_f32_e32 v72, v73, v74
	v_cvt_pk_bf16_f32 v71, v71, v72
	v_lshlrev_b32_e32 v72, 16, v100
	v_lshlrev_b32_e32 v73, 16, v104
	v_mul_f32_e32 v73, 0xbfb8aa3b, v73
	v_exp_f32_e32 v73, v73
	s_nop 0
	v_add_f32_e32 v73, 1.0, v73
	v_rcp_f32_e32 v73, v73
	s_nop 0
	v_fmac_f32_e32 v72, v66, v73
	v_and_b32_e32 v66, 0xffff0000, v100
	v_and_b32_e32 v73, 0xffff0000, v104
	v_mul_f32_e32 v73, 0xbfb8aa3b, v73
	v_exp_f32_e32 v73, v73
	s_nop 0
	v_add_f32_e32 v73, 1.0, v73
	v_rcp_f32_e32 v73, v73
	s_nop 0
	v_fmac_f32_e32 v66, v67, v73
	v_cvt_pk_bf16_f32 v72, v72, v66
	v_lshlrev_b32_e32 v66, 16, v101
	v_lshlrev_b32_e32 v67, 16, v105
	v_mul_f32_e32 v67, 0xbfb8aa3b, v67
	v_exp_f32_e32 v67, v67
	s_nop 0
	v_add_f32_e32 v67, 1.0, v67
	v_rcp_f32_e32 v67, v67
	s_nop 0
	v_fmac_f32_e32 v66, v68, v67
	v_and_b32_e32 v67, 0xffff0000, v101
	v_and_b32_e32 v68, 0xffff0000, v105
	v_mul_f32_e32 v68, 0xbfb8aa3b, v68
	v_exp_f32_e32 v68, v68
	s_nop 0
	v_add_f32_e32 v68, 1.0, v68
	v_rcp_f32_e32 v68, v68
	s_nop 0
	v_fmac_f32_e32 v67, v69, v68
	v_cvt_pk_bf16_f32 v73, v66, v67
	v_or_b32_e32 v66, 16, v114
	v_mov_b64_e32 v[68:69], s[18:19]
	global_store_dwordx4 v[130:131], v[70:73], off offset:256
	v_mad_i64_i32 v[68:69], s[50:51], v66, s81, v[68:69]
	v_lshl_add_u64 v[68:69], v[68:69], 0, v[172:173]
	global_load_dwordx4 v[74:77], v[68:69], off
	v_ashrrev_i32_e32 v67, 31, v66
	v_lshlrev_b64 v[66:67], 11, v[66:67]
	v_lshl_add_u64 v[66:67], s[12:13], 0, v[66:67]
	v_lshl_add_u64 v[98:99], v[66:67], 0, v[172:173]
	v_mov_b32_e32 v66, 0
	s_and_b64 vcc, exec, s[42:43]
	v_mov_b32_e32 v78, 0
	v_mov_b32_e32 v79, 0
	v_mov_b32_e32 v80, 0
	v_mov_b32_e32 v81, 0
	s_cbranch_vccnz .LBB0_1389
	global_load_dwordx4 v[78:81], v[98:99], off

; __device__ __forceinline__ unsigned cvt_pk_bf16(float lo, float hi) { unsigned r; asm volatile("v_cvt_pk_bf16_f32 %0, %1, %2" : "=v"(r) : "v"(lo), "v"(hi)); return r; }
; __device__ __forceinline__ float bf_lo(unsigned w) { return __uint_as_float(w << 16); }
; __device__ __forceinline__ float bf_hi(unsigned w) { return __uint_as_float(w & 0xffff0000u); }
;     __device__ __forceinline__ void operator()(const f32x4 (&acc)[2][2][4][2], const Unit& u, int wr, int wc, int fr, int fq) const {
;     ...
;             for (int bj = 0; bj < 2; ++bj) { const u32x4 gg = g[sl][bj], oo = o[sl][bj]; const f32x4 v0 = acc[ai][bj][m][0], v1 = acc[ai][bj][m][1]; u32x4 w;
;                 w.x = cvt_pk_bf16(bf_lo(oo.x) + bf_lo(gg.x) * v0[0], bf_hi(oo.x) + bf_hi(gg.x) * v0[1]);
;                 w.y = cvt_pk_bf16(bf_lo(oo.y) + bf_lo(gg.y) * v0[2], bf_hi(oo.y) + bf_hi(gg.y) * v0[3]);
;                 w.z = cvt_pk_bf16(bf_lo(oo.z) + bf_lo(gg.z) * v1[0], bf_hi(oo.z) + bf_hi(gg.z) * v1[1]);
;                 w.w = cvt_pk_bf16(bf_lo(oo.w) + bf_lo(gg.w) * v1[2], bf_hi(oo.w) + bf_hi(gg.w) * v1[3]);
;                 gst((u32x4*)(MIX + row * ldm + col0 + bj * HALF), w); }
.Lmy_gd_5:
	v_lshlrev_b32_e32 v100, 16, v94
	v_lshlrev_b32_e32 v101, 16, v90
	v_mul_f32_e32 v101, 0xbfb8aa3b, v101
	v_exp_f32_e32 v101, v101
	s_nop 0
	v_add_f32_e32 v101, 1.0, v101
	v_rcp_f32_e32 v101, v101
	s_nop 0
	v_fmac_f32_e32 v100, v62, v101
	v_and_b32_e32 v62, 0xffff0000, v94
	v_and_b32_e32 v90, 0xffff0000, v90
	v_mul_f32_e32 v90, 0xbfb8aa3b, v90
	v_exp_f32_e32 v90, v90
	s_nop 0
	v_add_f32_e32 v90, 1.0, v90
	v_rcp_f32_e32 v90, v90
	s_nop 0
	v_fmac_f32_e32 v62, v63, v90
	v_lshlrev_b32_e32 v63, 16, v95
	v_lshlrev_b32_e32 v90, 16, v91
	v_mul_f32_e32 v90, 0xbfb8aa3b, v90
	v_exp_f32_e32 v90, v90
	s_nop 0
	v_add_f32_e32 v90, 1.0, v90
	v_rcp_f32_e32 v90, v90
	s_nop 0
	v_fmac_f32_e32 v63, v64, v90
	v_and_b32_e32 v64, 0xffff0000, v95
	v_and_b32_e32 v90, 0xffff0000, v91
	v_mul_f32_e32 v90, 0xbfb8aa3b, v90
	v_exp_f32_e32 v90, v90
	s_nop 0
	v_add_f32_e32 v90, 1.0, v90
	v_rcp_f32_e32 v90, v90
	s_nop 0
	v_fmac_f32_e32 v64, v65, v90
	v_cvt_pk_bf16_f32 v62, v100, v62
	v_cvt_pk_bf16_f32 v63, v63, v64
	v_lshlrev_b32_e32 v64, 16, v96
	v_lshlrev_b32_e32 v65, 16, v92
	v_mul_f32_e32 v65, 0xbfb8aa3b, v65
	v_exp_f32_e32 v65, v65
	s_nop 0
	v_add_f32_e32 v65, 1.0, v65
	v_rcp_f32_e32 v65, v65
	s_nop 0
	v_fmac_f32_e32 v64, v58, v65
	v_and_b32_e32 v58, 0xffff0000, v96
	v_and_b32_e32 v65, 0xffff0000, v92
	v_mul_f32_e32 v65, 0xbfb8aa3b, v65
	v_exp_f32_e32 v65, v65
	s_nop 0
	v_add_f32_e32 v65, 1.0, v65
	v_rcp_f32_e32 v65, v65
	s_nop 0
	v_fmac_f32_e32 v58, v59, v65
	v_cvt_pk_bf16_f32 v64, v64, v58
	v_lshlrev_b32_e32 v58, 16, v97
	v_lshlrev_b32_e32 v59, 16, v93
	v_mul_f32_e32 v59, 0xbfb8aa3b, v59
	v_exp_f32_e32 v59, v59
	s_nop 0
	v_add_f32_e32 v59, 1.0, v59
	v_rcp_f32_e32 v59, v59
	s_nop 0
	v_fmac_f32_e32 v58, v60, v59
	v_and_b32_e32 v59, 0xffff0000, v97
	v_and_b32_e32 v60, 0xffff0000, v93
	v_mul_f32_e32 v60, 0xbfb8aa3b, v60
	v_exp_f32_e32 v60, v60
	s_nop 0
	v_add_f32_e32 v60, 1.0, v60
	v_rcp_f32_e32 v60, v60
	s_nop 0
	v_fmac_f32_e32 v59, v61, v60
	v_cvt_pk_bf16_f32 v65, v58, v59
	s_cbranch_vccnz .Lmy_gf_4
	s_waitcnt vmcnt(6)
	s_branch .Lmy_gd_4

; __device__ __forceinline__ unsigned cvt_pk_bf16(float lo, float hi) { unsigned r; asm volatile("v_cvt_pk_bf16_f32 %0, %1, %2" : "=v"(r) : "v"(lo), "v"(hi)); return r; }
; __device__ __forceinline__ float bf_lo(unsigned w) { return __uint_as_float(w << 16); }
; __device__ __forceinline__ float bf_hi(unsigned w) { return __uint_as_float(w & 0xffff0000u); }
; #define EG_LOAD(slot, it) do { const size_t row_ = (size_t)(row0 + ((it) >> 2) * HALF + ((it) & 3) * 16); _Pragma("unroll") for (int bj = 0; bj < 2; ++bj) { \
;             g[slot][bj] = gld((const u32x4*)(G + row_ * ldg + col0 + bj * HALF)); o[slot][bj] = (u32x4){0u, 0u, 0u, 0u}; if (!first) o[slot][bj] = gld((const u32x4*)(MIX + row_ * ldm + col0 + bj * HALF)); } } while (0)
;     __device__ __forceinline__ void operator()(const f32x4 (&acc)[2][2][4][2], const Unit& u, int wr, int wc, int fr, int fq) const {
;     ...
;         EG_LOAD(0, 0);
; #pragma unroll
;         for (int it = 0; it < 8; ++it) { const int ai = it >> 2, m = it & 3, sl = it & 1; const size_t row = (size_t)(row0 + ai * HALF + m * 16);
;             if (it + 1 < 8) EG_LOAD(sl ^ 1, it + 1);
; #pragma unroll
;             for (int bj = 0; bj < 2; ++bj) { const u32x4 gg = g[sl][bj], oo = o[sl][bj]; const f32x4 v0 = acc[ai][bj][m][0], v1 = acc[ai][bj][m][1]; u32x4 w;
;                 w.x = cvt_pk_bf16(bf_lo(oo.x) + bf_lo(gg.x) * v0[0], bf_hi(oo.x) + bf_hi(gg.x) * v0[1]);
;                 w.y = cvt_pk_bf16(bf_lo(oo.y) + bf_lo(gg.y) * v0[2], bf_hi(oo.y) + bf_hi(gg.y) * v0[3]);
;                 w.z = cvt_pk_bf16(bf_lo(oo.z) + bf_lo(gg.z) * v1[0], bf_hi(oo.z) + bf_hi(gg.z) * v1[1]);
;                 w.w = cvt_pk_bf16(bf_lo(oo.w) + bf_lo(gg.w) * v1[2], bf_hi(oo.w) + bf_hi(gg.w) * v1[3]);
;                 gst((u32x4*)(MIX + row * ldm + col0 + bj * HALF), w); }
.Lmy_gd_4:
	v_lshlrev_b32_e32 v58, 16, v82
	v_lshlrev_b32_e32 v59, 16, v86
	v_mul_f32_e32 v59, 0xbfb8aa3b, v59
	v_exp_f32_e32 v59, v59
	s_nop 0
	v_add_f32_e32 v59, 1.0, v59
	v_rcp_f32_e32 v59, v59
	s_nop 0
	v_fmac_f32_e32 v58, v54, v59
	v_and_b32_e32 v54, 0xffff0000, v82
	v_and_b32_e32 v59, 0xffff0000, v86
	v_mul_f32_e32 v59, 0xbfb8aa3b, v59
	v_exp_f32_e32 v59, v59
	s_nop 0
	v_add_f32_e32 v59, 1.0, v59
	v_rcp_f32_e32 v59, v59
	s_nop 0
	v_fmac_f32_e32 v54, v55, v59
	global_store_dwordx4 v[116:117], v[62:65], off
	v_cvt_pk_bf16_f32 v54, v58, v54
	v_lshlrev_b32_e32 v55, 16, v83
	v_lshlrev_b32_e32 v58, 16, v87
	v_mul_f32_e32 v58, 0xbfb8aa3b, v58
	v_exp_f32_e32 v58, v58
	s_nop 0
	v_add_f32_e32 v58, 1.0, v58
	v_rcp_f32_e32 v58, v58
	s_nop 0
	v_fmac_f32_e32 v55, v56, v58
	v_and_b32_e32 v56, 0xffff0000, v83
	v_and_b32_e32 v58, 0xffff0000, v87
	v_mul_f32_e32 v58, 0xbfb8aa3b, v58
	v_exp_f32_e32 v58, v58
	s_nop 0
	v_add_f32_e32 v58, 1.0, v58
	v_rcp_f32_e32 v58, v58
	s_nop 0
	v_fmac_f32_e32 v56, v57, v58
	v_cvt_pk_bf16_f32 v55, v55, v56
	v_lshlrev_b32_e32 v56, 16, v84
	v_lshlrev_b32_e32 v57, 16, v88
	v_mul_f32_e32 v57, 0xbfb8aa3b, v57
	v_exp_f32_e32 v57, v57
	s_nop 0
	v_add_f32_e32 v57, 1.0, v57
	v_rcp_f32_e32 v57, v57
	s_nop 0
	v_fmac_f32_e32 v56, v50, v57
	v_and_b32_e32 v50, 0xffff0000, v84
	v_and_b32_e32 v57, 0xffff0000, v88
	v_mul_f32_e32 v57, 0xbfb8aa3b, v57
	v_exp_f32_e32 v57, v57
	s_nop 0
	v_add_f32_e32 v57, 1.0, v57
	v_rcp_f32_e32 v57, v57
	s_nop 0
	v_fmac_f32_e32 v50, v51, v57
	v_cvt_pk_bf16_f32 v56, v56, v50
	v_lshlrev_b32_e32 v50, 16, v85
	v_lshlrev_b32_e32 v51, 16, v89
	v_mul_f32_e32 v51, 0xbfb8aa3b, v51
	v_exp_f32_e32 v51, v51
	s_nop 0
	v_add_f32_e32 v51, 1.0, v51
	v_rcp_f32_e32 v51, v51
	s_nop 0
	v_fmac_f32_e32 v50, v52, v51
	v_and_b32_e32 v51, 0xffff0000, v85
	v_and_b32_e32 v52, 0xffff0000, v89
	v_mul_f32_e32 v52, 0xbfb8aa3b, v52
	v_exp_f32_e32 v52, v52
	s_nop 0
	v_add_f32_e32 v52, 1.0, v52
	v_rcp_f32_e32 v52, v52
	s_nop 0
	v_fmac_f32_e32 v51, v53, v52
	v_cvt_pk_bf16_f32 v57, v50, v51
	v_or_b32_e32 v50, 32, v114
	v_mov_b64_e32 v[52:53], s[18:19]
	global_store_dwordx4 v[116:117], v[54:57], off offset:256
	v_mad_i64_i32 v[52:53], s[50:51], v50, s81, v[52:53]
	v_lshl_add_u64 v[52:53], v[52:53], 0, v[172:173]
	global_load_dwordx4 v[58:61], v[52:53], off
	v_ashrrev_i32_e32 v51, 31, v50
	v_lshlrev_b64 v[50:51], 11, v[50:51]
	v_lshl_add_u64 v[50:51], s[12:13], 0, v[50:51]
	v_lshl_add_u64 v[82:83], v[50:51], 0, v[172:173]
	v_mov_b32_e32 v50, 0
	s_and_b64 vcc, exec, s[42:43]
	v_mov_b32_e32 v62, 0
	v_mov_b32_e32 v63, 0
	v_mov_b32_e32 v64, 0
	v_mov_b32_e32 v65, 0
	s_cbranch_vccnz .LBB0_1393
	global_load_dwordx4 v[62:65], v[82:83], off

; __device__ __forceinline__ unsigned cvt_pk_bf16(float lo, float hi) { unsigned r; asm volatile("v_cvt_pk_bf16_f32 %0, %1, %2" : "=v"(r) : "v"(lo), "v"(hi)); return r; }
; __device__ __forceinline__ float bf_lo(unsigned w) { return __uint_as_float(w << 16); }
; __device__ __forceinline__ float bf_hi(unsigned w) { return __uint_as_float(w & 0xffff0000u); }
;     __device__ __forceinline__ void operator()(const f32x4 (&acc)[2][2][4][2], const Unit& u, int wr, int wc, int fr, int fq) const {
;     ...
;             for (int bj = 0; bj < 2; ++bj) { const u32x4 gg = g[sl][bj], oo = o[sl][bj]; const f32x4 v0 = acc[ai][bj][m][0], v1 = acc[ai][bj][m][1]; u32x4 w;
;                 w.x = cvt_pk_bf16(bf_lo(oo.x) + bf_lo(gg.x) * v0[0], bf_hi(oo.x) + bf_hi(gg.x) * v0[1]);
;                 w.y = cvt_pk_bf16(bf_lo(oo.y) + bf_lo(gg.y) * v0[2], bf_hi(oo.y) + bf_hi(gg.y) * v0[3]);
;                 w.z = cvt_pk_bf16(bf_lo(oo.z) + bf_lo(gg.z) * v1[0], bf_hi(oo.z) + bf_hi(gg.z) * v1[1]);
;                 w.w = cvt_pk_bf16(bf_lo(oo.w) + bf_lo(gg.w) * v1[2], bf_hi(oo.w) + bf_hi(gg.w) * v1[3]);
;                 gst((u32x4*)(MIX + row * ldm + col0 + bj * HALF), w); }
.Lmy_gd_3:
	v_lshlrev_b32_e32 v84, 16, v78
	v_lshlrev_b32_e32 v85, 16, v74
	v_mul_f32_e32 v85, 0xbfb8aa3b, v85
	v_exp_f32_e32 v85, v85
	s_nop 0
	v_add_f32_e32 v85, 1.0, v85
	v_rcp_f32_e32 v85, v85
	s_nop 0
	v_fmac_f32_e32 v84, v46, v85
	v_and_b32_e32 v46, 0xffff0000, v78
	v_and_b32_e32 v74, 0xffff0000, v74
	v_mul_f32_e32 v74, 0xbfb8aa3b, v74
	v_exp_f32_e32 v74, v74
	s_nop 0
	v_add_f32_e32 v74, 1.0, v74
	v_rcp_f32_e32 v74, v74
	s_nop 0
	v_fmac_f32_e32 v46, v47, v74
	v_lshlrev_b32_e32 v47, 16, v79
	v_lshlrev_b32_e32 v74, 16, v75
	v_mul_f32_e32 v74, 0xbfb8aa3b, v74
	v_exp_f32_e32 v74, v74
	s_nop 0
	v_add_f32_e32 v74, 1.0, v74
	v_rcp_f32_e32 v74, v74
	s_nop 0
	v_fmac_f32_e32 v47, v48, v74
	v_and_b32_e32 v48, 0xffff0000, v79
	v_and_b32_e32 v74, 0xffff0000, v75
	v_mul_f32_e32 v74, 0xbfb8aa3b, v74
	v_exp_f32_e32 v74, v74
	s_nop 0
	v_add_f32_e32 v74, 1.0, v74
	v_rcp_f32_e32 v74, v74
	s_nop 0
	v_fmac_f32_e32 v48, v49, v74
	v_cvt_pk_bf16_f32 v46, v84, v46
	v_cvt_pk_bf16_f32 v47, v47, v48
	v_lshlrev_b32_e32 v48, 16, v80
	v_lshlrev_b32_e32 v49, 16, v76
	v_mul_f32_e32 v49, 0xbfb8aa3b, v49
	v_exp_f32_e32 v49, v49
	s_nop 0
	v_add_f32_e32 v49, 1.0, v49
	v_rcp_f32_e32 v49, v49
	s_nop 0
	v_fmac_f32_e32 v48, v42, v49
	v_and_b32_e32 v42, 0xffff0000, v80
	v_and_b32_e32 v49, 0xffff0000, v76
	v_mul_f32_e32 v49, 0xbfb8aa3b, v49
	v_exp_f32_e32 v49, v49
	s_nop 0
	v_add_f32_e32 v49, 1.0, v49
	v_rcp_f32_e32 v49, v49
	s_nop 0
	v_fmac_f32_e32 v42, v43, v49
	v_cvt_pk_bf16_f32 v48, v48, v42
	v_lshlrev_b32_e32 v42, 16, v81
	v_lshlrev_b32_e32 v43, 16, v77
	v_mul_f32_e32 v43, 0xbfb8aa3b, v43
	v_exp_f32_e32 v43, v43
	s_nop 0
	v_add_f32_e32 v43, 1.0, v43
	v_rcp_f32_e32 v43, v43
	s_nop 0
	v_fmac_f32_e32 v42, v44, v43
	v_and_b32_e32 v43, 0xffff0000, v81
	v_and_b32_e32 v44, 0xffff0000, v77
	v_mul_f32_e32 v44, 0xbfb8aa3b, v44
	v_exp_f32_e32 v44, v44
	s_nop 0
	v_add_f32_e32 v44, 1.0, v44
	v_rcp_f32_e32 v44, v44
	s_nop 0
	v_fmac_f32_e32 v43, v45, v44
	v_cvt_pk_bf16_f32 v49, v42, v43
	s_cbranch_vccnz .Lmy_gf_2
	s_waitcnt vmcnt(6)
	s_branch .Lmy_gd_2

; __device__ __forceinline__ unsigned cvt_pk_bf16(float lo, float hi) { unsigned r; asm volatile("v_cvt_pk_bf16_f32 %0, %1, %2" : "=v"(r) : "v"(lo), "v"(hi)); return r; }
; __device__ __forceinline__ float bf_lo(unsigned w) { return __uint_as_float(w << 16); }
; __device__ __forceinline__ float bf_hi(unsigned w) { return __uint_as_float(w & 0xffff0000u); }
; #define EG_LOAD(slot, it) do { const size_t row_ = (size_t)(row0 + ((it) >> 2) * HALF + ((it) & 3) * 16); _Pragma("unroll") for (int bj = 0; bj < 2; ++bj) { \
;             g[slot][bj] = gld((const u32x4*)(G + row_ * ldg + col0 + bj * HALF)); o[slot][bj] = (u32x4){0u, 0u, 0u, 0u}; if (!first) o[slot][bj] = gld((const u32x4*)(MIX + row_ * ldm + col0 + bj * HALF)); } } while (0)
;     __device__ __forceinline__ void operator()(const f32x4 (&acc)[2][2][4][2], const Unit& u, int wr, int wc, int fr, int fq) const {
;     ...
;         EG_LOAD(0, 0);
; #pragma unroll
;         for (int it = 0; it < 8; ++it) { const int ai = it >> 2, m = it & 3, sl = it & 1; const size_t row = (size_t)(row0 + ai * HALF + m * 16);
;             if (it + 1 < 8) EG_LOAD(sl ^ 1, it + 1);
; #pragma unroll
;             for (int bj = 0; bj < 2; ++bj) { const u32x4 gg = g[sl][bj], oo = o[sl][bj]; const f32x4 v0 = acc[ai][bj][m][0], v1 = acc[ai][bj][m][1]; u32x4 w;
;                 w.x = cvt_pk_bf16(bf_lo(oo.x) + bf_lo(gg.x) * v0[0], bf_hi(oo.x) + bf_hi(gg.x) * v0[1]);
;                 w.y = cvt_pk_bf16(bf_lo(oo.y) + bf_lo(gg.y) * v0[2], bf_hi(oo.y) + bf_hi(gg.y) * v0[3]);
;                 w.z = cvt_pk_bf16(bf_lo(oo.z) + bf_lo(gg.z) * v1[0], bf_hi(oo.z) + bf_hi(gg.z) * v1[1]);
;                 w.w = cvt_pk_bf16(bf_lo(oo.w) + bf_lo(gg.w) * v1[2], bf_hi(oo.w) + bf_hi(gg.w) * v1[3]);
;                 gst((u32x4*)(MIX + row * ldm + col0 + bj * HALF), w); }
.Lmy_gd_2:
	v_lshlrev_b32_e32 v42, 16, v66
	v_lshlrev_b32_e32 v43, 16, v70
	v_mul_f32_e32 v43, 0xbfb8aa3b, v43
	v_exp_f32_e32 v43, v43
	s_nop 0
	v_add_f32_e32 v43, 1.0, v43
	v_rcp_f32_e32 v43, v43
	s_nop 0
	v_fmac_f32_e32 v42, v38, v43
	v_and_b32_e32 v38, 0xffff0000, v66
	v_and_b32_e32 v43, 0xffff0000, v70
	v_mul_f32_e32 v43, 0xbfb8aa3b, v43
	v_exp_f32_e32 v43, v43
	s_nop 0
	v_add_f32_e32 v43, 1.0, v43
	v_rcp_f32_e32 v43, v43
	s_nop 0
	v_fmac_f32_e32 v38, v39, v43
	global_store_dwordx4 v[98:99], v[46:49], off
	v_cvt_pk_bf16_f32 v38, v42, v38
	v_lshlrev_b32_e32 v39, 16, v67
	v_lshlrev_b32_e32 v42, 16, v71
	v_mul_f32_e32 v42, 0xbfb8aa3b, v42
	v_exp_f32_e32 v42, v42
	s_nop 0
	v_add_f32_e32 v42, 1.0, v42
	v_rcp_f32_e32 v42, v42
	s_nop 0
	v_fmac_f32_e32 v39, v40, v42
	v_and_b32_e32 v40, 0xffff0000, v67
	v_and_b32_e32 v42, 0xffff0000, v71
	v_mul_f32_e32 v42, 0xbfb8aa3b, v42
	v_exp_f32_e32 v42, v42
	s_nop 0
	v_add_f32_e32 v42, 1.0, v42
	v_rcp_f32_e32 v42, v42
	s_nop 0
	v_fmac_f32_e32 v40, v41, v42
	v_cvt_pk_bf16_f32 v39, v39, v40
	v_lshlrev_b32_e32 v40, 16, v68
	v_lshlrev_b32_e32 v41, 16, v72
	v_mul_f32_e32 v41, 0xbfb8aa3b, v41
	v_exp_f32_e32 v41, v41
	s_nop 0
	v_add_f32_e32 v41, 1.0, v41
	v_rcp_f32_e32 v41, v41
	s_nop 0
	v_fmac_f32_e32 v40, v34, v41
	v_and_b32_e32 v34, 0xffff0000, v68
	v_and_b32_e32 v41, 0xffff0000, v72
	v_mul_f32_e32 v41, 0xbfb8aa3b, v41
	v_exp_f32_e32 v41, v41
	s_nop 0
	v_add_f32_e32 v41, 1.0, v41
	v_rcp_f32_e32 v41, v41
	s_nop 0
	v_fmac_f32_e32 v34, v35, v41
	v_cvt_pk_bf16_f32 v40, v40, v34
	v_lshlrev_b32_e32 v34, 16, v69
	v_lshlrev_b32_e32 v35, 16, v73
	v_mul_f32_e32 v35, 0xbfb8aa3b, v35
	v_exp_f32_e32 v35, v35
	s_nop 0
	v_add_f32_e32 v35, 1.0, v35
	v_rcp_f32_e32 v35, v35
	s_nop 0
	v_fmac_f32_e32 v34, v36, v35
	v_and_b32_e32 v35, 0xffff0000, v69
	v_and_b32_e32 v36, 0xffff0000, v73
	v_mul_f32_e32 v36, 0xbfb8aa3b, v36
	v_exp_f32_e32 v36, v36
	s_nop 0
	v_add_f32_e32 v36, 1.0, v36
	v_rcp_f32_e32 v36, v36
	s_nop 0
	v_fmac_f32_e32 v35, v37, v36
	v_cvt_pk_bf16_f32 v41, v34, v35
	v_or_b32_e32 v34, 48, v114
	v_mov_b64_e32 v[36:37], s[18:19]
	global_store_dwordx4 v[98:99], v[38:41], off offset:256
	v_mad_i64_i32 v[36:37], s[50:51], v34, s81, v[36:37]
	v_lshl_add_u64 v[36:37], v[36:37], 0, v[172:173]
	global_load_dwordx4 v[42:45], v[36:37], off
	v_ashrrev_i32_e32 v35, 31, v34
	v_lshlrev_b64 v[34:35], 11, v[34:35]
	v_lshl_add_u64 v[34:35], s[12:13], 0, v[34:35]
	v_lshl_add_u64 v[66:67], v[34:35], 0, v[172:173]
	v_mov_b32_e32 v34, 0
	s_and_b64 vcc, exec, s[42:43]
	v_mov_b32_e32 v46, 0
	v_mov_b32_e32 v47, 0
	v_mov_b32_e32 v48, 0
	v_mov_b32_e32 v49, 0
	s_cbranch_vccnz .LBB0_1397
	global_load_dwordx4 v[46:49], v[66:67], off

; __device__ __forceinline__ unsigned cvt_pk_bf16(float lo, float hi) { unsigned r; asm volatile("v_cvt_pk_bf16_f32 %0, %1, %2" : "=v"(r) : "v"(lo), "v"(hi)); return r; }
; __device__ __forceinline__ float bf_lo(unsigned w) { return __uint_as_float(w << 16); }
; __device__ __forceinline__ float bf_hi(unsigned w) { return __uint_as_float(w & 0xffff0000u); }
;     __device__ __forceinline__ void operator()(const f32x4 (&acc)[2][2][4][2], const Unit& u, int wr, int wc, int fr, int fq) const {
;     ...
;             for (int bj = 0; bj < 2; ++bj) { const u32x4 gg = g[sl][bj], oo = o[sl][bj]; const f32x4 v0 = acc[ai][bj][m][0], v1 = acc[ai][bj][m][1]; u32x4 w;
;                 w.x = cvt_pk_bf16(bf_lo(oo.x) + bf_lo(gg.x) * v0[0], bf_hi(oo.x) + bf_hi(gg.x) * v0[1]);
;                 w.y = cvt_pk_bf16(bf_lo(oo.y) + bf_lo(gg.y) * v0[2], bf_hi(oo.y) + bf_hi(gg.y) * v0[3]);
;                 w.z = cvt_pk_bf16(bf_lo(oo.z) + bf_lo(gg.z) * v1[0], bf_hi(oo.z) + bf_hi(gg.z) * v1[1]);
;                 w.w = cvt_pk_bf16(bf_lo(oo.w) + bf_lo(gg.w) * v1[2], bf_hi(oo.w) + bf_hi(gg.w) * v1[3]);
;                 gst((u32x4*)(MIX + row * ldm + col0 + bj * HALF), w); }
.Lmy_gd_1:
	v_lshlrev_b32_e32 v68, 16, v62
	v_lshlrev_b32_e32 v69, 16, v58
	v_mul_f32_e32 v69, 0xbfb8aa3b, v69
	v_exp_f32_e32 v69, v69
	s_nop 0
	v_add_f32_e32 v69, 1.0, v69
	v_rcp_f32_e32 v69, v69
	s_nop 0
	v_fmac_f32_e32 v68, v30, v69
	v_and_b32_e32 v30, 0xffff0000, v62
	v_and_b32_e32 v58, 0xffff0000, v58
	v_mul_f32_e32 v58, 0xbfb8aa3b, v58
	v_exp_f32_e32 v58, v58
	s_nop 0
	v_add_f32_e32 v58, 1.0, v58
	v_rcp_f32_e32 v58, v58
	s_nop 0
	v_fmac_f32_e32 v30, v31, v58
	v_lshlrev_b32_e32 v31, 16, v63
	v_lshlrev_b32_e32 v58, 16, v59
	v_mul_f32_e32 v58, 0xbfb8aa3b, v58
	v_exp_f32_e32 v58, v58
	s_nop 0
	v_add_f32_e32 v58, 1.0, v58
	v_rcp_f32_e32 v58, v58
	s_nop 0
	v_fmac_f32_e32 v31, v32, v58
	v_and_b32_e32 v32, 0xffff0000, v63
	v_and_b32_e32 v58, 0xffff0000, v59
	v_mul_f32_e32 v58, 0xbfb8aa3b, v58
	v_exp_f32_e32 v58, v58
	s_nop 0
	v_add_f32_e32 v58, 1.0, v58
	v_rcp_f32_e32 v58, v58
	s_nop 0
	v_fmac_f32_e32 v32, v33, v58
	v_cvt_pk_bf16_f32 v30, v68, v30
	v_cvt_pk_bf16_f32 v31, v31, v32
	v_lshlrev_b32_e32 v32, 16, v64
	v_lshlrev_b32_e32 v33, 16, v60
	v_mul_f32_e32 v33, 0xbfb8aa3b, v33
	v_exp_f32_e32 v33, v33
	s_nop 0
	v_add_f32_e32 v33, 1.0, v33
	v_rcp_f32_e32 v33, v33
	s_nop 0
	v_fmac_f32_e32 v32, v26, v33
	v_and_b32_e32 v26, 0xffff0000, v64
	v_and_b32_e32 v33, 0xffff0000, v60
	v_mul_f32_e32 v33, 0xbfb8aa3b, v33
	v_exp_f32_e32 v33, v33
	s_nop 0
	v_add_f32_e32 v33, 1.0, v33
	v_rcp_f32_e32 v33, v33
	s_nop 0
	v_fmac_f32_e32 v26, v27, v33
	v_cvt_pk_bf16_f32 v32, v32, v26
	v_lshlrev_b32_e32 v26, 16, v65
	v_lshlrev_b32_e32 v27, 16, v61
	v_mul_f32_e32 v27, 0xbfb8aa3b, v27
	v_exp_f32_e32 v27, v27
	s_nop 0
	v_add_f32_e32 v27, 1.0, v27
	v_rcp_f32_e32 v27, v27
	s_nop 0
	v_fmac_f32_e32 v26, v28, v27
	v_and_b32_e32 v27, 0xffff0000, v65
	v_and_b32_e32 v28, 0xffff0000, v61
	v_mul_f32_e32 v28, 0xbfb8aa3b, v28
	v_exp_f32_e32 v28, v28
	s_nop 0
	v_add_f32_e32 v28, 1.0, v28
	v_rcp_f32_e32 v28, v28
	s_nop 0
	v_fmac_f32_e32 v27, v29, v28
	v_cvt_pk_bf16_f32 v33, v26, v27
	s_cbranch_vccnz .Lmy_gf_0
	s_waitcnt vmcnt(6)
	s_branch .Lmy_gd_0

; __device__ __forceinline__ unsigned cvt_pk_bf16(float lo, float hi) { unsigned r; asm volatile("v_cvt_pk_bf16_f32 %0, %1, %2" : "=v"(r) : "v"(lo), "v"(hi)); return r; }
; __device__ __forceinline__ float bf_lo(unsigned w) { return __uint_as_float(w << 16); }
; __device__ __forceinline__ float bf_hi(unsigned w) { return __uint_as_float(w & 0xffff0000u); }
; #define EG_LOAD(slot, it) do { const size_t row_ = (size_t)(row0 + ((it) >> 2) * HALF + ((it) & 3) * 16); _Pragma("unroll") for (int bj = 0; bj < 2; ++bj) { \
;             g[slot][bj] = gld((const u32x4*)(G + row_ * ldg + col0 + bj * HALF)); o[slot][bj] = (u32x4){0u, 0u, 0u, 0u}; if (!first) o[slot][bj] = gld((const u32x4*)(MIX + row_ * ldm + col0 + bj * HALF)); } } while (0)
;     __device__ __forceinline__ void operator()(const f32x4 (&acc)[2][2][4][2], const Unit& u, int wr, int wc, int fr, int fq) const {
;     ...
;         EG_LOAD(0, 0);
; #pragma unroll
;         for (int it = 0; it < 8; ++it) { const int ai = it >> 2, m = it & 3, sl = it & 1; const size_t row = (size_t)(row0 + ai * HALF + m * 16);
;             if (it + 1 < 8) EG_LOAD(sl ^ 1, it + 1);
; #pragma unroll
;             for (int bj = 0; bj < 2; ++bj) { const u32x4 gg = g[sl][bj], oo = o[sl][bj]; const f32x4 v0 = acc[ai][bj][m][0], v1 = acc[ai][bj][m][1]; u32x4 w;
;                 w.x = cvt_pk_bf16(bf_lo(oo.x) + bf_lo(gg.x) * v0[0], bf_hi(oo.x) + bf_hi(gg.x) * v0[1]);
;                 w.y = cvt_pk_bf16(bf_lo(oo.y) + bf_lo(gg.y) * v0[2], bf_hi(oo.y) + bf_hi(gg.y) * v0[3]);
;                 w.z = cvt_pk_bf16(bf_lo(oo.z) + bf_lo(gg.z) * v1[0], bf_hi(oo.z) + bf_hi(gg.z) * v1[1]);
;                 w.w = cvt_pk_bf16(bf_lo(oo.w) + bf_lo(gg.w) * v1[2], bf_hi(oo.w) + bf_hi(gg.w) * v1[3]);
;                 gst((u32x4*)(MIX + row * ldm + col0 + bj * HALF), w); }
; template <class Epi, bool ALIGN_EPI>
; __device__ __forceinline__ void gemm_phase(LAS unsigned char* lds, const Gemm g, const StaticOrder& S, const Epi& E) {
;     ...
;         if (!has_next) break;
; #pragma unroll
;         for (int a = 0; a < 2; ++a)
; #pragma unroll
;             for (int b = 0; b < 2; ++b)
; #pragma unroll
;                 for (int m = 0; m < 4; ++m)
; #pragma unroll
;                     for (int n = 0; n < 2; ++n) acc[a][b][m][n] = (f32x4){0.f, 0.f, 0.f, 0.f};
;         cur = nxt; cA = nA; cB = nB; ++ui;
;         if constexpr (ALIGN_EPI) { if (wr == 1) PG8_BAR; }
.Lmy_gd_0:
	v_lshlrev_b32_e32 v26, 16, v50
	v_lshlrev_b32_e32 v27, 16, v54
	v_mul_f32_e32 v27, 0xbfb8aa3b, v27
	v_exp_f32_e32 v27, v27
	s_nop 0
	v_add_f32_e32 v27, 1.0, v27
	v_rcp_f32_e32 v27, v27
	s_nop 0
	v_fmac_f32_e32 v26, v22, v27
	v_and_b32_e32 v22, 0xffff0000, v50
	v_and_b32_e32 v27, 0xffff0000, v54
	v_mul_f32_e32 v27, 0xbfb8aa3b, v27
	v_exp_f32_e32 v27, v27
	s_nop 0
	v_add_f32_e32 v27, 1.0, v27
	v_rcp_f32_e32 v27, v27
	s_nop 0
	v_fmac_f32_e32 v22, v23, v27
	global_store_dwordx4 v[82:83], v[30:33], off
	v_cvt_pk_bf16_f32 v22, v26, v22
	v_lshlrev_b32_e32 v23, 16, v51
	v_lshlrev_b32_e32 v26, 16, v55
	v_mul_f32_e32 v26, 0xbfb8aa3b, v26
	v_exp_f32_e32 v26, v26
	s_nop 0
	v_add_f32_e32 v26, 1.0, v26
	v_rcp_f32_e32 v26, v26
	s_nop 0
	v_fmac_f32_e32 v23, v24, v26
	v_and_b32_e32 v24, 0xffff0000, v51
	v_and_b32_e32 v26, 0xffff0000, v55
	v_mul_f32_e32 v26, 0xbfb8aa3b, v26
	v_exp_f32_e32 v26, v26
	s_nop 0
	v_add_f32_e32 v26, 1.0, v26
	v_rcp_f32_e32 v26, v26
	s_nop 0
	v_fmac_f32_e32 v24, v25, v26
	v_cvt_pk_bf16_f32 v23, v23, v24
	v_lshlrev_b32_e32 v24, 16, v52
	v_lshlrev_b32_e32 v25, 16, v56
	v_mul_f32_e32 v25, 0xbfb8aa3b, v25
	v_exp_f32_e32 v25, v25
	s_nop 0
	v_add_f32_e32 v25, 1.0, v25
	v_rcp_f32_e32 v25, v25
	s_nop 0
	v_fmac_f32_e32 v24, v14, v25
	v_and_b32_e32 v14, 0xffff0000, v52
	v_and_b32_e32 v25, 0xffff0000, v56
	v_mul_f32_e32 v25, 0xbfb8aa3b, v25
	v_exp_f32_e32 v25, v25
	s_nop 0
	v_add_f32_e32 v25, 1.0, v25
	v_rcp_f32_e32 v25, v25
	s_nop 0
	v_fmac_f32_e32 v14, v15, v25
	v_cvt_pk_bf16_f32 v24, v24, v14
	v_lshlrev_b32_e32 v14, 16, v53
	v_lshlrev_b32_e32 v15, 16, v57
	v_mul_f32_e32 v15, 0xbfb8aa3b, v15
	v_exp_f32_e32 v15, v15
	s_nop 0
	v_add_f32_e32 v15, 1.0, v15
	v_rcp_f32_e32 v15, v15
	s_nop 0
	v_fmac_f32_e32 v14, v16, v15
	v_and_b32_e32 v15, 0xffff0000, v53
	v_and_b32_e32 v16, 0xffff0000, v57
	v_mul_f32_e32 v16, 0xbfb8aa3b, v16
	v_exp_f32_e32 v16, v16
	s_nop 0
	v_add_f32_e32 v16, 1.0, v16
	v_rcp_f32_e32 v16, v16
	s_nop 0
	v_fmac_f32_e32 v15, v17, v16
	v_cvt_pk_bf16_f32 v25, v14, v15
	s_waitcnt vmcnt(2)
	v_lshlrev_b32_e32 v14, 16, v46
	v_lshlrev_b32_e32 v15, 16, v42
	v_mul_f32_e32 v15, 0xbfb8aa3b, v15
	v_exp_f32_e32 v15, v15
	s_nop 0
	v_add_f32_e32 v15, 1.0, v15
	v_rcp_f32_e32 v15, v15
	s_nop 0
	v_fmac_f32_e32 v14, v18, v15
	v_and_b32_e32 v15, 0xffff0000, v46
	v_and_b32_e32 v16, 0xffff0000, v42
	v_mul_f32_e32 v16, 0xbfb8aa3b, v16
	v_exp_f32_e32 v16, v16
	s_nop 0
	v_add_f32_e32 v16, 1.0, v16
	v_rcp_f32_e32 v16, v16
	s_nop 0
	global_store_dwordx4 v[82:83], v[22:25], off offset:256
	v_fmac_f32_e32 v15, v19, v16
	v_cvt_pk_bf16_f32 v14, v14, v15
	v_lshlrev_b32_e32 v15, 16, v47
	v_lshlrev_b32_e32 v16, 16, v43
	v_mul_f32_e32 v16, 0xbfb8aa3b, v16
	v_exp_f32_e32 v16, v16
	s_nop 0
	v_add_f32_e32 v16, 1.0, v16
	v_rcp_f32_e32 v16, v16
	s_nop 0
	v_fmac_f32_e32 v15, v20, v16
	v_and_b32_e32 v16, 0xffff0000, v47
	v_and_b32_e32 v17, 0xffff0000, v43
	v_mul_f32_e32 v17, 0xbfb8aa3b, v17
	v_exp_f32_e32 v17, v17
	s_nop 0
	v_add_f32_e32 v17, 1.0, v17
	v_rcp_f32_e32 v17, v17
	s_nop 0
	v_fmac_f32_e32 v16, v21, v17
	v_cvt_pk_bf16_f32 v15, v15, v16
	v_lshlrev_b32_e32 v16, 16, v48
	v_lshlrev_b32_e32 v17, 16, v44
	v_mul_f32_e32 v17, 0xbfb8aa3b, v17
	v_exp_f32_e32 v17, v17
	s_nop 0
	v_add_f32_e32 v17, 1.0, v17
	v_rcp_f32_e32 v17, v17
	s_nop 0
	v_fmac_f32_e32 v16, v10, v17
	v_and_b32_e32 v10, 0xffff0000, v48
	v_and_b32_e32 v17, 0xffff0000, v44
	v_mul_f32_e32 v17, 0xbfb8aa3b, v17
	v_exp_f32_e32 v17, v17
	s_nop 0
	v_add_f32_e32 v17, 1.0, v17
	v_rcp_f32_e32 v17, v17
	s_nop 0
	v_fmac_f32_e32 v10, v11, v17
	v_cvt_pk_bf16_f32 v16, v16, v10
	v_lshlrev_b32_e32 v10, 16, v49
	v_lshlrev_b32_e32 v11, 16, v45
	v_mul_f32_e32 v11, 0xbfb8aa3b, v11
	v_exp_f32_e32 v11, v11
	s_nop 0
	v_add_f32_e32 v11, 1.0, v11
	v_rcp_f32_e32 v11, v11
	s_nop 0
	v_fmac_f32_e32 v10, v12, v11
	v_and_b32_e32 v11, 0xffff0000, v49
	v_and_b32_e32 v12, 0xffff0000, v45
	v_mul_f32_e32 v12, 0xbfb8aa3b, v12
	v_exp_f32_e32 v12, v12
	s_nop 0
	v_add_f32_e32 v12, 1.0, v12
	v_rcp_f32_e32 v12, v12
	s_nop 0
	v_fmac_f32_e32 v11, v13, v12
	v_cvt_pk_bf16_f32 v17, v10, v11
	s_waitcnt vmcnt(2)
	v_lshlrev_b32_e32 v10, 16, v34
	v_lshlrev_b32_e32 v11, 16, v38
	v_mul_f32_e32 v11, 0xbfb8aa3b, v11
	v_exp_f32_e32 v11, v11
	s_nop 0
	v_add_f32_e32 v11, 1.0, v11
	v_rcp_f32_e32 v11, v11
	s_nop 0
	v_fmac_f32_e32 v10, v6, v11
	v_and_b32_e32 v6, 0xffff0000, v34
	v_and_b32_e32 v11, 0xffff0000, v38
	v_mul_f32_e32 v11, 0xbfb8aa3b, v11
	v_exp_f32_e32 v11, v11
	s_nop 0
	v_add_f32_e32 v11, 1.0, v11
	v_rcp_f32_e32 v11, v11
	s_nop 0
	v_fmac_f32_e32 v6, v7, v11
	global_store_dwordx4 v[66:67], v[14:17], off
	v_cvt_pk_bf16_f32 v6, v10, v6
	v_lshlrev_b32_e32 v7, 16, v35
	v_lshlrev_b32_e32 v10, 16, v39
	v_mul_f32_e32 v10, 0xbfb8aa3b, v10
	v_exp_f32_e32 v10, v10
	s_nop 0
	v_add_f32_e32 v10, 1.0, v10
	v_rcp_f32_e32 v10, v10
	s_nop 0
	v_fmac_f32_e32 v7, v8, v10
	v_and_b32_e32 v8, 0xffff0000, v35
	v_and_b32_e32 v10, 0xffff0000, v39
	v_mul_f32_e32 v10, 0xbfb8aa3b, v10
	v_exp_f32_e32 v10, v10
	s_nop 0
	v_add_f32_e32 v10, 1.0, v10
	v_rcp_f32_e32 v10, v10
	s_nop 0
	v_fmac_f32_e32 v8, v9, v10
	v_cvt_pk_bf16_f32 v7, v7, v8
	v_lshlrev_b32_e32 v8, 16, v36
	v_lshlrev_b32_e32 v9, 16, v40
	v_mul_f32_e32 v9, 0xbfb8aa3b, v9
	v_exp_f32_e32 v9, v9
	s_nop 0
	v_add_f32_e32 v9, 1.0, v9
	v_rcp_f32_e32 v9, v9
	s_nop 0
	v_fmac_f32_e32 v8, v0, v9
	v_and_b32_e32 v0, 0xffff0000, v36
	v_and_b32_e32 v9, 0xffff0000, v40
	v_mul_f32_e32 v9, 0xbfb8aa3b, v9
	v_exp_f32_e32 v9, v9
	s_nop 0
	v_add_f32_e32 v9, 1.0, v9
	v_rcp_f32_e32 v9, v9
	s_nop 0
	v_fmac_f32_e32 v0, v1, v9
	v_cvt_pk_bf16_f32 v8, v8, v0
	v_lshlrev_b32_e32 v0, 16, v37
	v_lshlrev_b32_e32 v1, 16, v41
	v_mul_f32_e32 v1, 0xbfb8aa3b, v1
	v_exp_f32_e32 v1, v1
	s_nop 0
	v_add_f32_e32 v1, 1.0, v1
	v_rcp_f32_e32 v1, v1
	s_nop 0
	v_fmac_f32_e32 v0, v2, v1
	v_and_b32_e32 v1, 0xffff0000, v37
	v_and_b32_e32 v2, 0xffff0000, v41
	v_mul_f32_e32 v2, 0xbfb8aa3b, v2
	v_exp_f32_e32 v2, v2
	s_nop 0
	v_add_f32_e32 v2, 1.0, v2
	v_rcp_f32_e32 v2, v2
	s_nop 0
	v_fmac_f32_e32 v1, v3, v2
	v_cvt_pk_bf16_f32 v9, v0, v1
	global_store_dwordx4 v[66:67], v[6:9], off offset:256
	s_andn2_b64 vcc, exec, s[40:41]
	s_mov_b64 s[40:41], -1
	s_cbranch_vccnz .LBB0_1356
	s_andn2_b64 vcc, exec, s[16:17]
	s_cbranch_vccnz .LBB0_1355
	s_barrier
	s_branch .LBB0_1355

; __device__ __forceinline__ float fsigmoid(float x) { return __builtin_amdgcn_rcpf(1.0f + __builtin_amdgcn_exp2f(-x * LOG2E)); }
; __device__ __forceinline__ void rows_rstd(const float* part, int row0, int fq, float (&rs)[2][4]) {
;     ...
;         for (int m = 0; m < 4; ++m) q[ai][m] = gld((const f32x4*)(part + (size_t)(row0 + ai * HALF + m * 16) * 16 + 4 * fq));
; #pragma unroll
;     for (int ai = 0; ai < 2; ++ai)
; #pragma unroll
;         for (int m = 0; m < 4; ++m) { float t = (q[ai][m].x + q[ai][m].y) + (q[ai][m].z + q[ai][m].w); t += __shfl_xor(t, 16); t += __shfl_xor(t, 32); rs[ai][m] = __builtin_amdgcn_rsqf(t * (1.0f / 1024.0f) + NORM_EPS); }
;     __device__ __forceinline__ void operator()(const f32x4 (&acc)[2][2][4][2], const Unit& u, int wr, int wc, int fr, int fq) const {
;         const int row0 = u.pm * BM + wr * 64 + fr, col0 = u.pn * BM + wc * 32 + 8 * fq; const bool sg = u.pn < nsig;
;         float rsv[2][4];
; #pragma unroll
;         for (int ai = 0; ai < 2; ++ai)
; #pragma unroll
;             for (int m = 0; m < 4; ++m) rsv[ai][m] = 1.0f;
;         if (part) rows_rstd(part, row0, fq, rsv);
;         const float ts = !qsc ? 1.0f : ((unsigned)(u.pn - 12) < 2u ? 0.125f * LOG2E : ((unsigned)(u.pn - 18) < 2u ? 0.08838834764831845f * LOG2E : 1.0f));
; #pragma unroll
;         for (int ai = 0; ai < 2; ++ai)
; #pragma unroll
;             for (int m = 0; m < 4; ++m) { const size_t row = (size_t)(row0 + ai * HALF + m * 16); bf16_t* rowp = O + row * ldc + col0; const float rs = rsv[ai][m] * ts;
; #pragma unroll
;                 for (int bj = 0; bj < 2; ++bj) { f32x4 v0 = acc[ai][bj][m][0] * rs, v1 = acc[ai][bj][m][1] * rs;
;                     if (sg) {
; #pragma unroll
;                         for (int e = 0; e < 4; ++e) { v0[e] = fsigmoid(v0[e]); v1[e] = fsigmoid(v1[e]); } }
.LBB0_1486:
	v_lshl_add_u32 v156, s22, 8, v164
	v_or_b32_e32 v154, 16, v156
	v_ashrrev_i32_e32 v157, 31, v156
	v_ashrrev_i32_e32 v155, 31, v154
	v_lshlrev_b64 v[142:143], 6, v[156:157]
	v_lshlrev_b64 v[144:145], 6, v[154:155]
	v_or_b32_e32 v152, 32, v156
	v_or_b32_e32 v150, 48, v156
	v_lshl_add_u64 v[142:143], v[136:137], 0, v[142:143]
	v_lshl_add_u64 v[144:145], v[136:137], 0, v[144:145]
	v_ashrrev_i32_e32 v153, 31, v152
	v_ashrrev_i32_e32 v151, 31, v150
	global_load_dwordx4 v[158:161], v[142:143], off
	global_load_dwordx4 v[168:171], v[144:145], off
	v_lshlrev_b64 v[142:143], 6, v[152:153]
	v_lshlrev_b64 v[144:145], 6, v[150:151]
	v_add_u32_e32 v148, 0x80, v156
	v_add_u32_e32 v146, 0x90, v156
	v_lshl_add_u64 v[142:143], v[136:137], 0, v[142:143]
	v_lshl_add_u64 v[144:145], v[136:137], 0, v[144:145]
	v_ashrrev_i32_e32 v149, 31, v148
	v_ashrrev_i32_e32 v147, 31, v146
	global_load_dwordx4 v[172:175], v[142:143], off
	global_load_dwordx4 v[176:179], v[144:145], off
	v_lshlrev_b64 v[142:143], 6, v[148:149]
	v_lshlrev_b64 v[144:145], 6, v[146:147]
	v_lshl_add_u64 v[142:143], v[136:137], 0, v[142:143]
	v_lshl_add_u64 v[144:145], v[136:137], 0, v[144:145]
	global_load_dwordx4 v[204:207], v[142:143], off
	global_load_dwordx4 v[208:211], v[144:145], off
	v_add_u32_e32 v144, 0xa0, v156
	v_ashrrev_i32_e32 v145, 31, v144
	v_lshlrev_b64 v[142:143], 6, v[144:145]
	v_lshl_add_u64 v[142:143], v[136:137], 0, v[142:143]
	global_load_dwordx4 v[212:215], v[142:143], off
	v_add_u32_e32 v142, 0xb0, v156
	v_ashrrev_i32_e32 v143, 31, v142
	v_lshlrev_b64 v[162:163], 6, v[142:143]
	v_lshl_add_u64 v[162:163], v[136:137], 0, v[162:163]
	global_load_dwordx4 v[216:219], v[162:163], off
	v_cmp_lt_i32_e32 vcc, v189, v184
	s_cmp_lt_i32 s20, 12
	s_cselect_b64 s[22:23], -1, 0
	v_cndmask_b32_e32 v143, v183, v189, vcc
	v_cmp_lt_i32_e32 vcc, v190, v184
	v_lshlrev_b32_e32 v143, 2, v143
	s_and_b32 s7, s20, -2
	v_cndmask_b32_e32 v145, v183, v190, vcc
	v_lshlrev_b32_e32 v147, 2, v145
	s_cmp_eq_u32 s7, 18
	s_cselect_b64 vcc, -1, 0
	s_cmp_lg_u32 s7, 12
	v_cndmask_b32_e32 v180, 1.0, v198, vcc
	s_cselect_b64 vcc, -1, 0
	s_cmp_gt_i32 s20, 11
	s_waitcnt vmcnt(0)
	v_mov_b32_e32 v162, v159
	v_mov_b32_e32 v163, v160
	v_mov_b32_e32 v159, v161
	v_pk_add_f32 v[158:159], v[162:163], v[158:159]
	v_add_f32_e32 v145, v168, v169
	v_add_f32_e32 v149, v170, v171
	v_add_f32_e32 v158, v158, v159
	v_add_f32_e32 v145, v145, v149
	v_add_f32_e32 v151, v172, v173
	v_add_f32_e32 v153, v174, v175
	v_add_f32_e32 v155, v176, v177
	v_add_f32_e32 v157, v178, v179
	v_add_f32_e32 v149, v151, v153
	v_add_f32_e32 v160, v204, v205
	v_add_f32_e32 v161, v206, v207
	v_add_f32_e32 v151, v155, v157
	ds_bpermute_b32 v157, v143, v158
	v_add_f32_e32 v153, v160, v161
	ds_bpermute_b32 v161, v143, v145
	v_add_f32_e32 v162, v208, v209
	v_add_f32_e32 v163, v210, v211
	s_waitcnt lgkmcnt(1)
	v_add_f32_e32 v158, v158, v157
	v_add_f32_e32 v168, v212, v213
	v_add_f32_e32 v169, v214, v215
	v_add_f32_e32 v170, v216, v217
	v_add_f32_e32 v171, v218, v219
	s_waitcnt lgkmcnt(0)
	v_add_f32_e32 v173, v145, v161
	ds_bpermute_b32 v145, v147, v158
	v_add_f32_e32 v155, v162, v163
	v_add_f32_e32 v159, v168, v169
	v_add_f32_e32 v160, v170, v171
	ds_bpermute_b32 v162, v143, v149
	ds_bpermute_b32 v163, v143, v151
	ds_bpermute_b32 v168, v143, v153
	ds_bpermute_b32 v175, v143, v155
	ds_bpermute_b32 v176, v143, v159
	ds_bpermute_b32 v143, v143, v160
	s_waitcnt lgkmcnt(6)
	v_add_f32_e32 v145, v158, v145
	v_fmamk_f32 v145, v145, 0x3a800000, v192
	s_waitcnt lgkmcnt(5)
	v_add_f32_e32 v171, v149, v162
	s_waitcnt lgkmcnt(4)
	v_add_f32_e32 v169, v151, v163
	s_waitcnt lgkmcnt(3)
	v_add_f32_e32 v157, v153, v168
	v_rsq_f32_e32 v158, v145
	s_waitcnt lgkmcnt(2)
	v_add_f32_e32 v153, v155, v175
	s_waitcnt lgkmcnt(1)
	v_add_f32_e32 v149, v159, v176
	s_waitcnt lgkmcnt(0)
	v_add_f32_e32 v145, v160, v143
	ds_bpermute_b32 v174, v147, v173
	ds_bpermute_b32 v172, v147, v171
	ds_bpermute_b32 v170, v147, v169
	ds_bpermute_b32 v168, v147, v157
	ds_bpermute_b32 v155, v147, v153
	ds_bpermute_b32 v151, v147, v149
	ds_bpermute_b32 v147, v147, v145
	v_cndmask_b32_e32 v143, v199, v180, vcc
	v_mul_f32_e32 v158, v143, v158
	v_pk_mul_f32 v[128:129], v[128:129], v[158:159] op_sel_hi:[1,0]
	v_pk_mul_f32 v[160:161], v[126:127], v[158:159] op_sel_hi:[1,0]
	v_pk_mul_f32 v[126:127], v[124:125], v[158:159] op_sel_hi:[1,0]
	v_pk_mul_f32 v[162:163], v[122:123], v[158:159] op_sel_hi:[1,0]
	s_branch .LBB0_1488
	v_mul_f32_e32 v122, 0xbfb8aa3b, v160
	v_exp_f32_e32 v122, v122
	v_mul_f32_e32 v123, 0xbfb8aa3b, v162
	v_exp_f32_e32 v123, v123
	v_mul_f32_e32 v124, 0xbfb8aa3b, v163
	v_add_f32_e32 v122, 1.0, v122
	v_rcp_f32_e32 v160, v122
	v_mul_f32_e32 v122, 0xbfb8aa3b, v161
	v_exp_f32_e32 v122, v122
	v_exp_f32_e32 v124, v124
	v_add_f32_e32 v123, 1.0, v123
	v_rcp_f32_e32 v162, v123
	v_add_f32_e32 v122, 1.0, v122
	v_mul_f32_e32 v123, 0xbfb8aa3b, v128
	v_rcp_f32_e32 v161, v122
	v_add_f32_e32 v122, 1.0, v124
	v_exp_f32_e32 v123, v123
	v_mul_f32_e32 v124, 0xbfb8aa3b, v126
	v_exp_f32_e32 v124, v124
	v_rcp_f32_e32 v163, v122
	v_add_f32_e32 v122, 1.0, v123
	v_mul_f32_e32 v123, 0xbfb8aa3b, v129
	v_rcp_f32_e32 v128, v122
	v_add_f32_e32 v122, 1.0, v124
	v_exp_f32_e32 v123, v123
	v_mul_f32_e32 v124, 0xbfb8aa3b, v127
	v_exp_f32_e32 v124, v124
	v_rcp_f32_e32 v126, v122
	v_add_f32_e32 v122, 1.0, v123
	v_rcp_f32_e32 v129, v122
	v_add_f32_e32 v122, 1.0, v124
	v_rcp_f32_e32 v127, v122
; __device__ __forceinline__ unsigned cvt_pk_bf16(float lo, float hi) { unsigned r; asm volatile("v_cvt_pk_bf16_f32 %0, %1, %2" : "=v"(r) : "v"(lo), "v"(hi)); return r; }
; __device__ __forceinline__ float fsigmoid(float x) { return __builtin_amdgcn_rcpf(1.0f + __builtin_amdgcn_exp2f(-x * LOG2E)); }
;     __device__ __forceinline__ void operator()(const f32x4 (&acc)[2][2][4][2], const Unit& u, int wr, int wc, int fr, int fq) const {
;     ...
;             for (int m = 0; m < 4; ++m) { const size_t row = (size_t)(row0 + ai * HALF + m * 16); bf16_t* rowp = O + row * ldc + col0; const float rs = rsv[ai][m] * ts;
; #pragma unroll
;                 for (int bj = 0; bj < 2; ++bj) { f32x4 v0 = acc[ai][bj][m][0] * rs, v1 = acc[ai][bj][m][1] * rs;
;                     if (sg) {
; #pragma unroll
;                         for (int e = 0; e < 4; ++e) { v0[e] = fsigmoid(v0[e]); v1[e] = fsigmoid(v1[e]); } }
;                     u32x4 w; w.x = cvt_pk_bf16(v0[0], v0[1]); w.y = cvt_pk_bf16(v0[2], v0[3]); w.z = cvt_pk_bf16(v1[0], v1[1]); w.w = cvt_pk_bf16(v1[2], v1[3]);
;                     gst((u32x4*)(rowp + bj * HALF), w); } }
.LBB0_1488:
	v_lshl_or_b32 v122, s20, 8, v166
	v_mov_b64_e32 v[124:125], s[10:11]
	v_cvt_pk_bf16_f32 v160, v160, v161
	v_cvt_pk_bf16_f32 v161, v128, v129
	v_cvt_pk_bf16_f32 v162, v162, v163
	v_cvt_pk_bf16_f32 v163, v126, v127
	v_mov_b32_e32 v126, v158
	v_mov_b32_e32 v127, v158
	v_mov_b32_e32 v159, v158
	v_ashrrev_i32_e32 v123, 31, v122
	v_mad_i64_i32 v[124:125], s[20:21], v156, s81, v[124:125]
	v_pk_mul_f32 v[120:121], v[120:121], v[126:127]
	v_pk_mul_f32 v[116:117], v[116:117], v[126:127]
	v_cndmask_b32_e64 v126, 0, 1, s[22:23]
	v_lshl_add_u64 v[124:125], v[122:123], 1, v[124:125]
	v_pk_mul_f32 v[118:119], v[118:119], v[158:159]
	v_cmp_ne_u32_e64 s[42:43], 1, v126
	s_andn2_b64 vcc, exec, s[22:23]
	v_pk_mul_f32 v[114:115], v[114:115], v[158:159]
	global_store_dwordx4 v[124:125], v[160:163], off
	s_branch .LBB0_1490
	v_mul_f32_e32 v118, 0xbfb8aa3b, v118
	v_mul_f32_e32 v114, 0xbfb8aa3b, v114
	v_mul_f32_e32 v119, 0xbfb8aa3b, v119
	v_mul_f32_e32 v115, 0xbfb8aa3b, v115
	v_mul_f32_e32 v120, 0xbfb8aa3b, v120
	v_mul_f32_e32 v116, 0xbfb8aa3b, v116
	v_mul_f32_e32 v121, 0xbfb8aa3b, v121
	v_mul_f32_e32 v117, 0xbfb8aa3b, v117
	v_exp_f32_e32 v118, v118
	v_exp_f32_e32 v114, v114
	v_exp_f32_e32 v119, v119
	v_exp_f32_e32 v115, v115
	v_exp_f32_e32 v120, v120
	v_exp_f32_e32 v116, v116
	v_exp_f32_e32 v121, v121
	v_exp_f32_e32 v117, v117
	v_add_f32_e32 v118, 1.0, v118
	v_add_f32_e32 v114, 1.0, v114
	v_add_f32_e32 v119, 1.0, v119
	v_add_f32_e32 v115, 1.0, v115
	v_add_f32_e32 v120, 1.0, v120
	v_add_f32_e32 v116, 1.0, v116
	v_add_f32_e32 v121, 1.0, v121
	v_add_f32_e32 v117, 1.0, v117
	v_rcp_f32_e32 v118, v118
	v_rcp_f32_e32 v114, v114
	v_rcp_f32_e32 v119, v119
	v_rcp_f32_e32 v115, v115
	v_rcp_f32_e32 v120, v120
	v_rcp_f32_e32 v116, v116
	v_rcp_f32_e32 v121, v121
	v_rcp_f32_e32 v117, v117
.LBB0_1490:
	s_waitcnt lgkmcnt(6)
	v_add_f32_e32 v126, v173, v174
	v_fmamk_f32 v126, v126, 0x3a800000, v192
	v_rsq_f32_e32 v126, v126
	v_cvt_pk_bf16_f32 v118, v118, v119
	v_cvt_pk_bf16_f32 v119, v120, v121
	v_cvt_pk_bf16_f32 v120, v114, v115
	v_cvt_pk_bf16_f32 v121, v116, v117
	s_and_b64 vcc, exec, s[42:43]
	v_mul_f32_e32 v114, v143, v126
	v_pk_mul_f32 v[112:113], v[112:113], v[114:115] op_sel_hi:[1,0]
	v_pk_mul_f32 v[110:111], v[110:111], v[114:115] op_sel_hi:[1,0]
	v_pk_mul_f32 v[108:109], v[108:109], v[114:115] op_sel_hi:[1,0]
	v_pk_mul_f32 v[116:117], v[106:107], v[114:115] op_sel_hi:[1,0]
	global_store_dwordx4 v[124:125], v[118:121], off offset:256
	s_branch .LBB0_1492
	v_mul_f32_e32 v106, 0xbfb8aa3b, v110
	v_exp_f32_e32 v106, v106
	v_mul_f32_e32 v107, 0xbfb8aa3b, v116
	v_exp_f32_e32 v107, v107
	v_mul_f32_e32 v108, 0xbfb8aa3b, v108
	v_add_f32_e32 v106, 1.0, v106
	v_rcp_f32_e32 v110, v106
	v_mul_f32_e32 v106, 0xbfb8aa3b, v111
	v_add_f32_e32 v107, 1.0, v107
	v_exp_f32_e32 v106, v106
	v_mul_f32_e32 v111, 0xbfb8aa3b, v117
	v_exp_f32_e32 v115, v111
	v_rcp_f32_e32 v116, v107
	v_mul_f32_e32 v107, 0xbfb8aa3b, v112
	v_exp_f32_e32 v107, v107
	v_exp_f32_e32 v108, v108
	v_add_f32_e32 v106, 1.0, v106
	v_rcp_f32_e32 v111, v106
	v_add_f32_e32 v106, 1.0, v115
	v_rcp_f32_e32 v117, v106
	v_add_f32_e32 v106, 1.0, v107
	v_mul_f32_e32 v107, 0xbfb8aa3b, v113
	v_rcp_f32_e32 v112, v106
	v_add_f32_e32 v106, 1.0, v108
	v_exp_f32_e32 v107, v107
	v_mul_f32_e32 v108, 0xbfb8aa3b, v109
	v_exp_f32_e32 v109, v108
	v_rcp_f32_e32 v108, v106
	v_add_f32_e32 v106, 1.0, v107
	v_rcp_f32_e32 v113, v106
	v_add_f32_e32 v106, 1.0, v109
	v_rcp_f32_e32 v109, v106
.LBB0_1492:
	v_mov_b64_e32 v[106:107], s[10:11]
	v_mov_b32_e32 v115, v114
	v_mad_i64_i32 v[106:107], s[20:21], v154, s81, v[106:107]
	v_cvt_pk_bf16_f32 v110, v110, v111
	v_cvt_pk_bf16_f32 v111, v112, v113
	v_cvt_pk_bf16_f32 v112, v116, v117
	v_cvt_pk_bf16_f32 v113, v108, v109
	v_mov_b32_e32 v108, v114
	v_mov_b32_e32 v109, v114
	v_lshl_add_u64 v[106:107], v[122:123], 1, v[106:107]
	v_pk_mul_f32 v[104:105], v[104:105], v[108:109]
	v_pk_mul_f32 v[102:103], v[102:103], v[114:115]
	v_pk_mul_f32 v[100:101], v[100:101], v[108:109]
	s_and_b64 vcc, exec, s[42:43]
	v_pk_mul_f32 v[98:99], v[98:99], v[114:115]
	global_store_dwordx4 v[106:107], v[110:113], off
	s_branch .LBB0_1494
	v_mul_f32_e32 v102, 0xbfb8aa3b, v102
	v_mul_f32_e32 v98, 0xbfb8aa3b, v98
	v_mul_f32_e32 v103, 0xbfb8aa3b, v103
	v_mul_f32_e32 v99, 0xbfb8aa3b, v99
	v_mul_f32_e32 v104, 0xbfb8aa3b, v104
	v_mul_f32_e32 v100, 0xbfb8aa3b, v100
	v_mul_f32_e32 v105, 0xbfb8aa3b, v105
	v_mul_f32_e32 v101, 0xbfb8aa3b, v101
	v_exp_f32_e32 v102, v102
	v_exp_f32_e32 v98, v98
	v_exp_f32_e32 v103, v103
	v_exp_f32_e32 v99, v99
	v_exp_f32_e32 v104, v104
	v_exp_f32_e32 v100, v100
	v_exp_f32_e32 v105, v105
	v_exp_f32_e32 v101, v101
	v_add_f32_e32 v102, 1.0, v102
	v_add_f32_e32 v98, 1.0, v98
	v_add_f32_e32 v103, 1.0, v103
	v_add_f32_e32 v99, 1.0, v99
	v_add_f32_e32 v104, 1.0, v104
	v_add_f32_e32 v100, 1.0, v100
	v_add_f32_e32 v105, 1.0, v105
	v_add_f32_e32 v101, 1.0, v101
	v_rcp_f32_e32 v102, v102
	v_rcp_f32_e32 v98, v98
	v_rcp_f32_e32 v103, v103
	v_rcp_f32_e32 v99, v99
	v_rcp_f32_e32 v104, v104
	v_rcp_f32_e32 v100, v100
	v_rcp_f32_e32 v105, v105
	v_rcp_f32_e32 v101, v101
; __device__ __forceinline__ unsigned cvt_pk_bf16(float lo, float hi) { unsigned r; asm volatile("v_cvt_pk_bf16_f32 %0, %1, %2" : "=v"(r) : "v"(lo), "v"(hi)); return r; }
; __device__ __forceinline__ float fsigmoid(float x) { return __builtin_amdgcn_rcpf(1.0f + __builtin_amdgcn_exp2f(-x * LOG2E)); }
;     __device__ __forceinline__ void operator()(const f32x4 (&acc)[2][2][4][2], const Unit& u, int wr, int wc, int fr, int fq) const {
;     ...
;             for (int m = 0; m < 4; ++m) { const size_t row = (size_t)(row0 + ai * HALF + m * 16); bf16_t* rowp = O + row * ldc + col0; const float rs = rsv[ai][m] * ts;
; #pragma unroll
;                 for (int bj = 0; bj < 2; ++bj) { f32x4 v0 = acc[ai][bj][m][0] * rs, v1 = acc[ai][bj][m][1] * rs;
;                     if (sg) {
; #pragma unroll
;                         for (int e = 0; e < 4; ++e) { v0[e] = fsigmoid(v0[e]); v1[e] = fsigmoid(v1[e]); } }
;                     u32x4 w; w.x = cvt_pk_bf16(v0[0], v0[1]); w.y = cvt_pk_bf16(v0[2], v0[3]); w.z = cvt_pk_bf16(v1[0], v1[1]); w.w = cvt_pk_bf16(v1[2], v1[3]);
;                     gst((u32x4*)(rowp + bj * HALF), w); } }
.LBB0_1494:
	s_waitcnt lgkmcnt(5)
	v_add_f32_e32 v108, v171, v172
	v_fmamk_f32 v108, v108, 0x3a800000, v192
	v_rsq_f32_e32 v108, v108
	v_cvt_pk_bf16_f32 v102, v102, v103
	v_cvt_pk_bf16_f32 v103, v104, v105
	v_cvt_pk_bf16_f32 v104, v98, v99
	v_cvt_pk_bf16_f32 v105, v100, v101
	s_and_b64 vcc, exec, s[42:43]
	v_mul_f32_e32 v98, v143, v108
	v_pk_mul_f32 v[96:97], v[96:97], v[98:99] op_sel_hi:[1,0]
	v_pk_mul_f32 v[94:95], v[94:95], v[98:99] op_sel_hi:[1,0]
	v_pk_mul_f32 v[92:93], v[92:93], v[98:99] op_sel_hi:[1,0]
	v_pk_mul_f32 v[100:101], v[90:91], v[98:99] op_sel_hi:[1,0]
	global_store_dwordx4 v[106:107], v[102:105], off offset:256
	s_branch .LBB0_1496
	v_mul_f32_e32 v90, 0xbfb8aa3b, v94
	v_exp_f32_e32 v90, v90
	v_mul_f32_e32 v91, 0xbfb8aa3b, v100
	v_exp_f32_e32 v91, v91
	v_mul_f32_e32 v92, 0xbfb8aa3b, v92
	v_add_f32_e32 v90, 1.0, v90
	v_rcp_f32_e32 v94, v90
	v_mul_f32_e32 v90, 0xbfb8aa3b, v95
	v_add_f32_e32 v91, 1.0, v91
	v_exp_f32_e32 v90, v90
	v_mul_f32_e32 v95, 0xbfb8aa3b, v101
	v_exp_f32_e32 v99, v95
	v_rcp_f32_e32 v100, v91
	v_mul_f32_e32 v91, 0xbfb8aa3b, v96
	v_exp_f32_e32 v91, v91
	v_exp_f32_e32 v92, v92
	v_add_f32_e32 v90, 1.0, v90
	v_rcp_f32_e32 v95, v90
	v_add_f32_e32 v90, 1.0, v99
	v_rcp_f32_e32 v101, v90
	v_add_f32_e32 v90, 1.0, v91
	v_mul_f32_e32 v91, 0xbfb8aa3b, v97
	v_rcp_f32_e32 v96, v90
	v_add_f32_e32 v90, 1.0, v92
	v_exp_f32_e32 v91, v91
	v_mul_f32_e32 v92, 0xbfb8aa3b, v93
	v_exp_f32_e32 v93, v92
	v_rcp_f32_e32 v92, v90
	v_add_f32_e32 v90, 1.0, v91
	v_rcp_f32_e32 v97, v90
	v_add_f32_e32 v90, 1.0, v93
	v_rcp_f32_e32 v93, v90
.LBB0_1496:
	v_mov_b64_e32 v[90:91], s[10:11]
	v_mov_b32_e32 v99, v98
	v_mad_i64_i32 v[90:91], s[20:21], v152, s81, v[90:91]
	v_cvt_pk_bf16_f32 v94, v94, v95
	v_cvt_pk_bf16_f32 v95, v96, v97
	v_cvt_pk_bf16_f32 v96, v100, v101
	v_cvt_pk_bf16_f32 v97, v92, v93
	v_mov_b32_e32 v92, v98
	v_mov_b32_e32 v93, v98
	v_lshl_add_u64 v[90:91], v[122:123], 1, v[90:91]
	v_pk_mul_f32 v[88:89], v[88:89], v[92:93]
	v_pk_mul_f32 v[86:87], v[86:87], v[98:99]
	v_pk_mul_f32 v[84:85], v[84:85], v[92:93]
	s_and_b64 vcc, exec, s[42:43]
	v_pk_mul_f32 v[82:83], v[82:83], v[98:99]
	global_store_dwordx4 v[90:91], v[94:97], off
	s_branch .LBB0_1498
	v_mul_f32_e32 v86, 0xbfb8aa3b, v86
	v_mul_f32_e32 v82, 0xbfb8aa3b, v82
	v_mul_f32_e32 v87, 0xbfb8aa3b, v87
	v_mul_f32_e32 v83, 0xbfb8aa3b, v83
	v_mul_f32_e32 v88, 0xbfb8aa3b, v88
	v_mul_f32_e32 v84, 0xbfb8aa3b, v84
	v_mul_f32_e32 v89, 0xbfb8aa3b, v89
	v_mul_f32_e32 v85, 0xbfb8aa3b, v85
	v_exp_f32_e32 v86, v86
	v_exp_f32_e32 v82, v82
	v_exp_f32_e32 v87, v87
	v_exp_f32_e32 v83, v83
	v_exp_f32_e32 v88, v88
	v_exp_f32_e32 v84, v84
	v_exp_f32_e32 v89, v89
	v_exp_f32_e32 v85, v85
	v_add_f32_e32 v86, 1.0, v86
	v_add_f32_e32 v82, 1.0, v82
	v_add_f32_e32 v87, 1.0, v87
	v_add_f32_e32 v83, 1.0, v83
	v_add_f32_e32 v88, 1.0, v88
	v_add_f32_e32 v84, 1.0, v84
	v_add_f32_e32 v89, 1.0, v89
	v_add_f32_e32 v85, 1.0, v85
	v_rcp_f32_e32 v86, v86
	v_rcp_f32_e32 v82, v82
	v_rcp_f32_e32 v87, v87
	v_rcp_f32_e32 v83, v83
	v_rcp_f32_e32 v88, v88
	v_rcp_f32_e32 v84, v84
	v_rcp_f32_e32 v89, v89
	v_rcp_f32_e32 v85, v85
.LBB0_1498:
	s_waitcnt lgkmcnt(4)
	v_add_f32_e32 v92, v169, v170
	v_fmamk_f32 v92, v92, 0x3a800000, v192
	v_rsq_f32_e32 v92, v92
	v_cvt_pk_bf16_f32 v86, v86, v87
	v_cvt_pk_bf16_f32 v87, v88, v89
	v_cvt_pk_bf16_f32 v88, v82, v83
	v_cvt_pk_bf16_f32 v89, v84, v85
	s_and_b64 vcc, exec, s[42:43]
	v_mul_f32_e32 v82, v143, v92
	v_pk_mul_f32 v[80:81], v[80:81], v[82:83] op_sel_hi:[1,0]
	v_pk_mul_f32 v[78:79], v[78:79], v[82:83] op_sel_hi:[1,0]
	v_pk_mul_f32 v[76:77], v[76:77], v[82:83] op_sel_hi:[1,0]
	v_pk_mul_f32 v[84:85], v[74:75], v[82:83] op_sel_hi:[1,0]
	global_store_dwordx4 v[90:91], v[86:89], off offset:256
	s_branch .LBB0_1500
	v_mul_f32_e32 v74, 0xbfb8aa3b, v78
	v_exp_f32_e32 v74, v74
	v_mul_f32_e32 v75, 0xbfb8aa3b, v84
	v_exp_f32_e32 v75, v75
	v_mul_f32_e32 v76, 0xbfb8aa3b, v76
	v_add_f32_e32 v74, 1.0, v74
	v_rcp_f32_e32 v78, v74
	v_mul_f32_e32 v74, 0xbfb8aa3b, v79
	v_add_f32_e32 v75, 1.0, v75
	v_exp_f32_e32 v74, v74
	v_mul_f32_e32 v79, 0xbfb8aa3b, v85
	v_exp_f32_e32 v83, v79
	v_rcp_f32_e32 v84, v75
	v_mul_f32_e32 v75, 0xbfb8aa3b, v80
	v_exp_f32_e32 v75, v75
	v_exp_f32_e32 v76, v76
	v_add_f32_e32 v74, 1.0, v74
	v_rcp_f32_e32 v79, v74
	v_add_f32_e32 v74, 1.0, v83
	v_rcp_f32_e32 v85, v74
	v_add_f32_e32 v74, 1.0, v75
	v_mul_f32_e32 v75, 0xbfb8aa3b, v81
	v_rcp_f32_e32 v80, v74
	v_add_f32_e32 v74, 1.0, v76
	v_exp_f32_e32 v75, v75
	v_mul_f32_e32 v76, 0xbfb8aa3b, v77
	v_exp_f32_e32 v77, v76
	v_rcp_f32_e32 v76, v74
	v_add_f32_e32 v74, 1.0, v75
	v_rcp_f32_e32 v81, v74
	v_add_f32_e32 v74, 1.0, v77
	v_rcp_f32_e32 v77, v74
.LBB0_1500:
	v_mov_b64_e32 v[74:75], s[10:11]
	v_mov_b32_e32 v83, v82
	v_mad_i64_i32 v[74:75], s[20:21], v150, s81, v[74:75]
	v_cvt_pk_bf16_f32 v78, v78, v79
	v_cvt_pk_bf16_f32 v79, v80, v81
	v_cvt_pk_bf16_f32 v80, v84, v85
	v_cvt_pk_bf16_f32 v81, v76, v77
	v_mov_b32_e32 v76, v82
	v_mov_b32_e32 v77, v82
	v_lshl_add_u64 v[74:75], v[122:123], 1, v[74:75]
	v_pk_mul_f32 v[72:73], v[72:73], v[76:77]
	v_pk_mul_f32 v[70:71], v[70:71], v[82:83]
	v_pk_mul_f32 v[68:69], v[68:69], v[76:77]
	s_and_b64 vcc, exec, s[42:43]
	v_pk_mul_f32 v[66:67], v[66:67], v[82:83]
	global_store_dwordx4 v[74:75], v[78:81], off
	s_branch .LBB0_1502
	v_mul_f32_e32 v70, 0xbfb8aa3b, v70
	v_mul_f32_e32 v66, 0xbfb8aa3b, v66
	v_mul_f32_e32 v71, 0xbfb8aa3b, v71
	v_mul_f32_e32 v67, 0xbfb8aa3b, v67
	v_mul_f32_e32 v72, 0xbfb8aa3b, v72
	v_mul_f32_e32 v68, 0xbfb8aa3b, v68
	v_mul_f32_e32 v73, 0xbfb8aa3b, v73
	v_mul_f32_e32 v69, 0xbfb8aa3b, v69
	v_exp_f32_e32 v70, v70
	v_exp_f32_e32 v66, v66
	v_exp_f32_e32 v71, v71
	v_exp_f32_e32 v67, v67
	v_exp_f32_e32 v72, v72
	v_exp_f32_e32 v68, v68
	v_exp_f32_e32 v73, v73
	v_exp_f32_e32 v69, v69
	v_add_f32_e32 v70, 1.0, v70
	v_add_f32_e32 v66, 1.0, v66
	v_add_f32_e32 v71, 1.0, v71
	v_add_f32_e32 v67, 1.0, v67
	v_add_f32_e32 v72, 1.0, v72
	v_add_f32_e32 v68, 1.0, v68
	v_add_f32_e32 v73, 1.0, v73
	v_add_f32_e32 v69, 1.0, v69
	v_rcp_f32_e32 v70, v70
	v_rcp_f32_e32 v66, v66
	v_rcp_f32_e32 v71, v71
	v_rcp_f32_e32 v67, v67
	v_rcp_f32_e32 v72, v72
	v_rcp_f32_e32 v68, v68
	v_rcp_f32_e32 v73, v73
	v_rcp_f32_e32 v69, v69
; __device__ __forceinline__ unsigned cvt_pk_bf16(float lo, float hi) { unsigned r; asm volatile("v_cvt_pk_bf16_f32 %0, %1, %2" : "=v"(r) : "v"(lo), "v"(hi)); return r; }
; __device__ __forceinline__ float fsigmoid(float x) { return __builtin_amdgcn_rcpf(1.0f + __builtin_amdgcn_exp2f(-x * LOG2E)); }
;     __device__ __forceinline__ void operator()(const f32x4 (&acc)[2][2][4][2], const Unit& u, int wr, int wc, int fr, int fq) const {
;     ...
;             for (int m = 0; m < 4; ++m) { const size_t row = (size_t)(row0 + ai * HALF + m * 16); bf16_t* rowp = O + row * ldc + col0; const float rs = rsv[ai][m] * ts;
; #pragma unroll
;                 for (int bj = 0; bj < 2; ++bj) { f32x4 v0 = acc[ai][bj][m][0] * rs, v1 = acc[ai][bj][m][1] * rs;
;                     if (sg) {
; #pragma unroll
;                         for (int e = 0; e < 4; ++e) { v0[e] = fsigmoid(v0[e]); v1[e] = fsigmoid(v1[e]); } }
;                     u32x4 w; w.x = cvt_pk_bf16(v0[0], v0[1]); w.y = cvt_pk_bf16(v0[2], v0[3]); w.z = cvt_pk_bf16(v1[0], v1[1]); w.w = cvt_pk_bf16(v1[2], v1[3]);
;                     gst((u32x4*)(rowp + bj * HALF), w); } }
.LBB0_1502:
	s_waitcnt lgkmcnt(3)
	v_add_f32_e32 v76, v157, v168
	v_fmamk_f32 v76, v76, 0x3a800000, v192
	v_rsq_f32_e32 v76, v76
	v_cvt_pk_bf16_f32 v70, v70, v71
	v_cvt_pk_bf16_f32 v71, v72, v73
	v_cvt_pk_bf16_f32 v72, v66, v67
	v_cvt_pk_bf16_f32 v73, v68, v69
	s_and_b64 vcc, exec, s[42:43]
	v_mul_f32_e32 v66, v143, v76
	v_pk_mul_f32 v[64:65], v[64:65], v[66:67] op_sel_hi:[1,0]
	v_pk_mul_f32 v[62:63], v[62:63], v[66:67] op_sel_hi:[1,0]
	v_pk_mul_f32 v[60:61], v[60:61], v[66:67] op_sel_hi:[1,0]
	v_pk_mul_f32 v[68:69], v[58:59], v[66:67] op_sel_hi:[1,0]
	global_store_dwordx4 v[74:75], v[70:73], off offset:256
	s_branch .LBB0_1504
	v_mul_f32_e32 v58, 0xbfb8aa3b, v62
	v_exp_f32_e32 v58, v58
	v_mul_f32_e32 v59, 0xbfb8aa3b, v68
	v_exp_f32_e32 v59, v59
	v_mul_f32_e32 v60, 0xbfb8aa3b, v60
	v_add_f32_e32 v58, 1.0, v58
	v_rcp_f32_e32 v62, v58
	v_mul_f32_e32 v58, 0xbfb8aa3b, v63
	v_add_f32_e32 v59, 1.0, v59
	v_exp_f32_e32 v58, v58
	v_mul_f32_e32 v63, 0xbfb8aa3b, v69
	v_exp_f32_e32 v67, v63
	v_rcp_f32_e32 v68, v59
	v_mul_f32_e32 v59, 0xbfb8aa3b, v64
	v_exp_f32_e32 v59, v59
	v_exp_f32_e32 v60, v60
	v_add_f32_e32 v58, 1.0, v58
	v_rcp_f32_e32 v63, v58
	v_add_f32_e32 v58, 1.0, v67
	v_rcp_f32_e32 v69, v58
	v_add_f32_e32 v58, 1.0, v59
	v_mul_f32_e32 v59, 0xbfb8aa3b, v65
	v_rcp_f32_e32 v64, v58
	v_add_f32_e32 v58, 1.0, v60
	v_exp_f32_e32 v59, v59
	v_mul_f32_e32 v60, 0xbfb8aa3b, v61
	v_exp_f32_e32 v61, v60
	v_rcp_f32_e32 v60, v58
	v_add_f32_e32 v58, 1.0, v59
	v_rcp_f32_e32 v65, v58
	v_add_f32_e32 v58, 1.0, v61
	v_rcp_f32_e32 v61, v58
.LBB0_1504:
	v_mov_b64_e32 v[58:59], s[10:11]
	v_mov_b32_e32 v67, v66
	v_mad_i64_i32 v[58:59], s[20:21], v148, s81, v[58:59]
	v_cvt_pk_bf16_f32 v62, v62, v63
	v_cvt_pk_bf16_f32 v63, v64, v65
	v_cvt_pk_bf16_f32 v64, v68, v69
	v_cvt_pk_bf16_f32 v65, v60, v61
	v_mov_b32_e32 v60, v66
	v_mov_b32_e32 v61, v66
	v_lshl_add_u64 v[58:59], v[122:123], 1, v[58:59]
	v_pk_mul_f32 v[56:57], v[56:57], v[60:61]
	v_pk_mul_f32 v[54:55], v[54:55], v[66:67]
	v_pk_mul_f32 v[52:53], v[52:53], v[60:61]
	s_and_b64 vcc, exec, s[42:43]
	v_pk_mul_f32 v[50:51], v[50:51], v[66:67]
	global_store_dwordx4 v[58:59], v[62:65], off
	s_branch .LBB0_1506
	v_mul_f32_e32 v54, 0xbfb8aa3b, v54
	v_mul_f32_e32 v50, 0xbfb8aa3b, v50
	v_mul_f32_e32 v55, 0xbfb8aa3b, v55
	v_mul_f32_e32 v51, 0xbfb8aa3b, v51
	v_mul_f32_e32 v56, 0xbfb8aa3b, v56
	v_mul_f32_e32 v52, 0xbfb8aa3b, v52
	v_mul_f32_e32 v57, 0xbfb8aa3b, v57
	v_mul_f32_e32 v53, 0xbfb8aa3b, v53
	v_exp_f32_e32 v54, v54
	v_exp_f32_e32 v50, v50
	v_exp_f32_e32 v55, v55
	v_exp_f32_e32 v51, v51
	v_exp_f32_e32 v56, v56
	v_exp_f32_e32 v52, v52
	v_exp_f32_e32 v57, v57
	v_exp_f32_e32 v53, v53
	v_add_f32_e32 v54, 1.0, v54
	v_add_f32_e32 v50, 1.0, v50
	v_add_f32_e32 v55, 1.0, v55
	v_add_f32_e32 v51, 1.0, v51
	v_add_f32_e32 v56, 1.0, v56
	v_add_f32_e32 v52, 1.0, v52
	v_add_f32_e32 v57, 1.0, v57
	v_add_f32_e32 v53, 1.0, v53
	v_rcp_f32_e32 v54, v54
	v_rcp_f32_e32 v50, v50
	v_rcp_f32_e32 v55, v55
	v_rcp_f32_e32 v51, v51
	v_rcp_f32_e32 v56, v56
	v_rcp_f32_e32 v52, v52
	v_rcp_f32_e32 v57, v57
	v_rcp_f32_e32 v53, v53
.LBB0_1506:
	s_waitcnt lgkmcnt(2)
	v_add_f32_e32 v60, v153, v155
	v_fmamk_f32 v60, v60, 0x3a800000, v192
	v_rsq_f32_e32 v60, v60
	v_cvt_pk_bf16_f32 v54, v54, v55
	v_cvt_pk_bf16_f32 v55, v56, v57
	v_cvt_pk_bf16_f32 v56, v50, v51
	v_cvt_pk_bf16_f32 v57, v52, v53
	s_and_b64 vcc, exec, s[42:43]
	v_mul_f32_e32 v50, v143, v60
	v_pk_mul_f32 v[48:49], v[48:49], v[50:51] op_sel_hi:[1,0]
	v_pk_mul_f32 v[46:47], v[46:47], v[50:51] op_sel_hi:[1,0]
	v_pk_mul_f32 v[44:45], v[44:45], v[50:51] op_sel_hi:[1,0]
	v_pk_mul_f32 v[52:53], v[42:43], v[50:51] op_sel_hi:[1,0]
	global_store_dwordx4 v[58:59], v[54:57], off offset:256
	s_branch .LBB0_1508
	v_mul_f32_e32 v42, 0xbfb8aa3b, v46
	v_exp_f32_e32 v42, v42
	v_mul_f32_e32 v43, 0xbfb8aa3b, v52
	v_exp_f32_e32 v43, v43
	v_mul_f32_e32 v44, 0xbfb8aa3b, v44
	v_add_f32_e32 v42, 1.0, v42
	v_rcp_f32_e32 v46, v42
	v_mul_f32_e32 v42, 0xbfb8aa3b, v47
	v_add_f32_e32 v43, 1.0, v43
	v_exp_f32_e32 v42, v42
	v_mul_f32_e32 v47, 0xbfb8aa3b, v53
	v_exp_f32_e32 v51, v47
	v_rcp_f32_e32 v52, v43
	v_mul_f32_e32 v43, 0xbfb8aa3b, v48
	v_exp_f32_e32 v43, v43
	v_exp_f32_e32 v44, v44
	v_add_f32_e32 v42, 1.0, v42
	v_rcp_f32_e32 v47, v42
	v_add_f32_e32 v42, 1.0, v51
	v_rcp_f32_e32 v53, v42
	v_add_f32_e32 v42, 1.0, v43
	v_mul_f32_e32 v43, 0xbfb8aa3b, v49
	v_rcp_f32_e32 v48, v42
	v_add_f32_e32 v42, 1.0, v44
	v_exp_f32_e32 v43, v43
	v_mul_f32_e32 v44, 0xbfb8aa3b, v45
	v_exp_f32_e32 v45, v44
	v_rcp_f32_e32 v44, v42
	v_add_f32_e32 v42, 1.0, v43
	v_rcp_f32_e32 v49, v42
	v_add_f32_e32 v42, 1.0, v45
	v_rcp_f32_e32 v45, v42
.LBB0_1508:
	v_mov_b64_e32 v[42:43], s[10:11]
	v_mov_b32_e32 v51, v50
	v_mad_i64_i32 v[42:43], s[20:21], v146, s81, v[42:43]
	v_cvt_pk_bf16_f32 v46, v46, v47
	v_cvt_pk_bf16_f32 v47, v48, v49
	v_cvt_pk_bf16_f32 v48, v52, v53
	v_cvt_pk_bf16_f32 v49, v44, v45
	v_mov_b32_e32 v44, v50
	v_mov_b32_e32 v45, v50
	v_lshl_add_u64 v[42:43], v[122:123], 1, v[42:43]
	v_pk_mul_f32 v[40:41], v[40:41], v[44:45]
	v_pk_mul_f32 v[38:39], v[38:39], v[50:51]
	v_pk_mul_f32 v[36:37], v[36:37], v[44:45]
	s_and_b64 vcc, exec, s[42:43]
	v_pk_mul_f32 v[34:35], v[34:35], v[50:51]
	global_store_dwordx4 v[42:43], v[46:49], off
	s_branch .LBB0_1510
	v_mul_f32_e32 v38, 0xbfb8aa3b, v38
	v_mul_f32_e32 v34, 0xbfb8aa3b, v34
	v_mul_f32_e32 v39, 0xbfb8aa3b, v39
	v_mul_f32_e32 v35, 0xbfb8aa3b, v35
	v_mul_f32_e32 v40, 0xbfb8aa3b, v40
	v_mul_f32_e32 v36, 0xbfb8aa3b, v36
	v_mul_f32_e32 v41, 0xbfb8aa3b, v41
	v_mul_f32_e32 v37, 0xbfb8aa3b, v37
	v_exp_f32_e32 v38, v38
	v_exp_f32_e32 v34, v34
	v_exp_f32_e32 v39, v39
	v_exp_f32_e32 v35, v35
	v_exp_f32_e32 v40, v40
	v_exp_f32_e32 v36, v36
	v_exp_f32_e32 v41, v41
	v_exp_f32_e32 v37, v37
	v_add_f32_e32 v38, 1.0, v38
	v_add_f32_e32 v34, 1.0, v34
	v_add_f32_e32 v39, 1.0, v39
	v_add_f32_e32 v35, 1.0, v35
	v_add_f32_e32 v40, 1.0, v40
	v_add_f32_e32 v36, 1.0, v36
	v_add_f32_e32 v41, 1.0, v41
	v_add_f32_e32 v37, 1.0, v37
	v_rcp_f32_e32 v38, v38
	v_rcp_f32_e32 v34, v34
	v_rcp_f32_e32 v39, v39
	v_rcp_f32_e32 v35, v35
	v_rcp_f32_e32 v40, v40
	v_rcp_f32_e32 v36, v36
	v_rcp_f32_e32 v41, v41
	v_rcp_f32_e32 v37, v37
; __device__ __forceinline__ unsigned cvt_pk_bf16(float lo, float hi) { unsigned r; asm volatile("v_cvt_pk_bf16_f32 %0, %1, %2" : "=v"(r) : "v"(lo), "v"(hi)); return r; }
; __device__ __forceinline__ float fsigmoid(float x) { return __builtin_amdgcn_rcpf(1.0f + __builtin_amdgcn_exp2f(-x * LOG2E)); }
;     __device__ __forceinline__ void operator()(const f32x4 (&acc)[2][2][4][2], const Unit& u, int wr, int wc, int fr, int fq) const {
;     ...
;             for (int m = 0; m < 4; ++m) { const size_t row = (size_t)(row0 + ai * HALF + m * 16); bf16_t* rowp = O + row * ldc + col0; const float rs = rsv[ai][m] * ts;
; #pragma unroll
;                 for (int bj = 0; bj < 2; ++bj) { f32x4 v0 = acc[ai][bj][m][0] * rs, v1 = acc[ai][bj][m][1] * rs;
;                     if (sg) {
; #pragma unroll
;                         for (int e = 0; e < 4; ++e) { v0[e] = fsigmoid(v0[e]); v1[e] = fsigmoid(v1[e]); } }
;                     u32x4 w; w.x = cvt_pk_bf16(v0[0], v0[1]); w.y = cvt_pk_bf16(v0[2], v0[3]); w.z = cvt_pk_bf16(v1[0], v1[1]); w.w = cvt_pk_bf16(v1[2], v1[3]);
;                     gst((u32x4*)(rowp + bj * HALF), w); } }
.LBB0_1510:
	s_waitcnt lgkmcnt(1)
	v_add_f32_e32 v44, v149, v151
	v_fmamk_f32 v44, v44, 0x3a800000, v192
	v_rsq_f32_e32 v44, v44
	v_cvt_pk_bf16_f32 v38, v38, v39
	v_cvt_pk_bf16_f32 v39, v40, v41
	v_cvt_pk_bf16_f32 v40, v34, v35
	v_cvt_pk_bf16_f32 v41, v36, v37
	s_and_b64 vcc, exec, s[42:43]
	v_mul_f32_e32 v34, v143, v44
	v_pk_mul_f32 v[32:33], v[32:33], v[34:35] op_sel_hi:[1,0]
	v_pk_mul_f32 v[30:31], v[30:31], v[34:35] op_sel_hi:[1,0]
	v_pk_mul_f32 v[28:29], v[28:29], v[34:35] op_sel_hi:[1,0]
	v_pk_mul_f32 v[36:37], v[26:27], v[34:35] op_sel_hi:[1,0]
	global_store_dwordx4 v[42:43], v[38:41], off offset:256
	s_branch .LBB0_1512
	v_mul_f32_e32 v26, 0xbfb8aa3b, v30
	v_exp_f32_e32 v26, v26
	v_mul_f32_e32 v27, 0xbfb8aa3b, v36
	v_exp_f32_e32 v27, v27
	v_mul_f32_e32 v28, 0xbfb8aa3b, v28
	v_add_f32_e32 v26, 1.0, v26
	v_rcp_f32_e32 v30, v26
	v_mul_f32_e32 v26, 0xbfb8aa3b, v31
	v_add_f32_e32 v27, 1.0, v27
	v_exp_f32_e32 v26, v26
	v_mul_f32_e32 v31, 0xbfb8aa3b, v37
	v_exp_f32_e32 v35, v31
	v_rcp_f32_e32 v36, v27
	v_mul_f32_e32 v27, 0xbfb8aa3b, v32
	v_exp_f32_e32 v27, v27
	v_exp_f32_e32 v28, v28
	v_add_f32_e32 v26, 1.0, v26
	v_rcp_f32_e32 v31, v26
	v_add_f32_e32 v26, 1.0, v35
	v_rcp_f32_e32 v37, v26
	v_add_f32_e32 v26, 1.0, v27
	v_mul_f32_e32 v27, 0xbfb8aa3b, v33
	v_rcp_f32_e32 v32, v26
	v_add_f32_e32 v26, 1.0, v28
	v_exp_f32_e32 v27, v27
	v_mul_f32_e32 v28, 0xbfb8aa3b, v29
	v_exp_f32_e32 v29, v28
	v_rcp_f32_e32 v28, v26
	v_add_f32_e32 v26, 1.0, v27
	v_rcp_f32_e32 v33, v26
	v_add_f32_e32 v26, 1.0, v29
	v_rcp_f32_e32 v29, v26
.LBB0_1512:
	v_mov_b64_e32 v[26:27], s[10:11]
	v_mov_b32_e32 v35, v34
	v_mad_i64_i32 v[26:27], s[20:21], v144, s81, v[26:27]
	v_cvt_pk_bf16_f32 v30, v30, v31
	v_cvt_pk_bf16_f32 v31, v32, v33
	v_cvt_pk_bf16_f32 v32, v36, v37
	v_cvt_pk_bf16_f32 v33, v28, v29
	v_mov_b32_e32 v28, v34
	v_mov_b32_e32 v29, v34
	v_lshl_add_u64 v[26:27], v[122:123], 1, v[26:27]
	v_pk_mul_f32 v[24:25], v[24:25], v[28:29]
	v_pk_mul_f32 v[22:23], v[22:23], v[34:35]
	v_pk_mul_f32 v[20:21], v[20:21], v[28:29]
	s_and_b64 vcc, exec, s[42:43]
	v_pk_mul_f32 v[18:19], v[18:19], v[34:35]
	global_store_dwordx4 v[26:27], v[30:33], off
	s_branch .LBB0_1514
	v_mul_f32_e32 v22, 0xbfb8aa3b, v22
	v_mul_f32_e32 v18, 0xbfb8aa3b, v18
	v_mul_f32_e32 v23, 0xbfb8aa3b, v23
	v_mul_f32_e32 v19, 0xbfb8aa3b, v19
	v_mul_f32_e32 v24, 0xbfb8aa3b, v24
	v_mul_f32_e32 v20, 0xbfb8aa3b, v20
	v_mul_f32_e32 v25, 0xbfb8aa3b, v25
	v_mul_f32_e32 v21, 0xbfb8aa3b, v21
	v_exp_f32_e32 v22, v22
	v_exp_f32_e32 v18, v18
	v_exp_f32_e32 v23, v23
	v_exp_f32_e32 v19, v19
	v_exp_f32_e32 v24, v24
	v_exp_f32_e32 v20, v20
	v_exp_f32_e32 v25, v25
	v_exp_f32_e32 v21, v21
	v_add_f32_e32 v22, 1.0, v22
	v_add_f32_e32 v18, 1.0, v18
	v_add_f32_e32 v23, 1.0, v23
	v_add_f32_e32 v19, 1.0, v19
	v_add_f32_e32 v24, 1.0, v24
	v_add_f32_e32 v20, 1.0, v20
	v_add_f32_e32 v25, 1.0, v25
	v_add_f32_e32 v21, 1.0, v21
	v_rcp_f32_e32 v22, v22
	v_rcp_f32_e32 v18, v18
	v_rcp_f32_e32 v23, v23
	v_rcp_f32_e32 v19, v19
	v_rcp_f32_e32 v24, v24
	v_rcp_f32_e32 v20, v20
	v_rcp_f32_e32 v25, v25
	v_rcp_f32_e32 v21, v21
.LBB0_1514:
	s_waitcnt lgkmcnt(0)
	v_add_f32_e32 v28, v145, v147
	v_fmamk_f32 v28, v28, 0x3a800000, v192
	v_rsq_f32_e32 v28, v28
	v_cvt_pk_bf16_f32 v22, v22, v23
	v_cvt_pk_bf16_f32 v23, v24, v25
	v_cvt_pk_bf16_f32 v24, v18, v19
	v_cvt_pk_bf16_f32 v25, v20, v21
	s_and_b64 vcc, exec, s[42:43]
	v_mul_f32_e32 v18, v143, v28
	v_pk_mul_f32 v[16:17], v[16:17], v[18:19] op_sel_hi:[1,0]
	v_pk_mul_f32 v[14:15], v[14:15], v[18:19] op_sel_hi:[1,0]
	v_pk_mul_f32 v[12:13], v[12:13], v[18:19] op_sel_hi:[1,0]
	v_pk_mul_f32 v[20:21], v[10:11], v[18:19] op_sel_hi:[1,0]
	global_store_dwordx4 v[26:27], v[22:25], off offset:256
	s_branch .LBB0_1516
	v_mul_f32_e32 v10, 0xbfb8aa3b, v14
	v_exp_f32_e32 v10, v10
	v_mul_f32_e32 v11, 0xbfb8aa3b, v20
	v_exp_f32_e32 v11, v11
	v_mul_f32_e32 v12, 0xbfb8aa3b, v12
	v_add_f32_e32 v10, 1.0, v10
	v_rcp_f32_e32 v14, v10
	v_mul_f32_e32 v10, 0xbfb8aa3b, v15
	v_add_f32_e32 v11, 1.0, v11
	v_exp_f32_e32 v10, v10
	v_mul_f32_e32 v15, 0xbfb8aa3b, v21
	v_exp_f32_e32 v19, v15
	v_rcp_f32_e32 v20, v11
	v_mul_f32_e32 v11, 0xbfb8aa3b, v16
	v_exp_f32_e32 v11, v11
	v_exp_f32_e32 v12, v12
	v_add_f32_e32 v10, 1.0, v10
	v_rcp_f32_e32 v15, v10
	v_add_f32_e32 v10, 1.0, v19
	v_rcp_f32_e32 v21, v10
	v_add_f32_e32 v10, 1.0, v11
	v_mul_f32_e32 v11, 0xbfb8aa3b, v17
	v_rcp_f32_e32 v16, v10
	v_add_f32_e32 v10, 1.0, v12
	v_exp_f32_e32 v11, v11
	v_mul_f32_e32 v12, 0xbfb8aa3b, v13
	v_exp_f32_e32 v13, v12
	v_rcp_f32_e32 v12, v10
	v_add_f32_e32 v10, 1.0, v11
	v_rcp_f32_e32 v17, v10
	v_add_f32_e32 v10, 1.0, v13
	v_rcp_f32_e32 v13, v10
.LBB0_1516:
	v_mov_b64_e32 v[10:11], s[10:11]
	v_mov_b32_e32 v19, v18
	v_mad_i64_i32 v[10:11], s[20:21], v142, s81, v[10:11]
	v_cvt_pk_bf16_f32 v14, v14, v15
	v_cvt_pk_bf16_f32 v15, v16, v17
	v_cvt_pk_bf16_f32 v16, v20, v21
	v_cvt_pk_bf16_f32 v17, v12, v13
	v_mov_b32_e32 v12, v18
	v_mov_b32_e32 v13, v18
	v_lshl_add_u64 v[10:11], v[122:123], 1, v[10:11]
	v_pk_mul_f32 v[8:9], v[8:9], v[12:13]
	v_pk_mul_f32 v[6:7], v[6:7], v[18:19]
	v_pk_mul_f32 v[2:3], v[2:3], v[12:13]
	s_and_b64 vcc, exec, s[42:43]
	v_pk_mul_f32 v[0:1], v[0:1], v[18:19]
	global_store_dwordx4 v[10:11], v[14:17], off
	s_branch .LBB0_1518
	v_mul_f32_e32 v6, 0xbfb8aa3b, v6
	v_mul_f32_e32 v0, 0xbfb8aa3b, v0
	v_mul_f32_e32 v7, 0xbfb8aa3b, v7
	v_mul_f32_e32 v1, 0xbfb8aa3b, v1
	v_mul_f32_e32 v8, 0xbfb8aa3b, v8
	v_mul_f32_e32 v2, 0xbfb8aa3b, v2
	v_mul_f32_e32 v9, 0xbfb8aa3b, v9
	v_mul_f32_e32 v3, 0xbfb8aa3b, v3
	v_exp_f32_e32 v6, v6
	v_exp_f32_e32 v0, v0
	v_exp_f32_e32 v7, v7
	v_exp_f32_e32 v1, v1
	v_exp_f32_e32 v8, v8
	v_exp_f32_e32 v2, v2
	v_exp_f32_e32 v9, v9
	v_exp_f32_e32 v3, v3
	v_add_f32_e32 v6, 1.0, v6
	v_add_f32_e32 v0, 1.0, v0
	v_add_f32_e32 v7, 1.0, v7
	v_add_f32_e32 v1, 1.0, v1
	v_add_f32_e32 v8, 1.0, v8
	v_add_f32_e32 v2, 1.0, v2
	v_add_f32_e32 v9, 1.0, v9
	v_add_f32_e32 v3, 1.0, v3
	v_rcp_f32_e32 v6, v6
	v_rcp_f32_e32 v0, v0
	v_rcp_f32_e32 v7, v7
	v_rcp_f32_e32 v1, v1
	v_rcp_f32_e32 v8, v8
	v_rcp_f32_e32 v2, v2
	v_rcp_f32_e32 v9, v9
	v_rcp_f32_e32 v3, v3
